# weight convert: layer-3 mlp_w1/mlp_w2 (18% of the convert work) deferred to the 192 workgroups that have no tile in the layer-2 K/V GEMM; layers 0-2 via hand-pipelined fast path
# speedup vs baseline: 1.0135x; 1.0135x over previous
.LBB0_7:
	s_load_dwordx16 s[8:23], s[0:1], 0x40
	s_lshl_b32 s3, s29, 3
	s_mov_b64 s[0:1], s[94:95]
	v_mov_b32_e32 v2, v193
	s_lshl_b32 s86, s96, 3
	s_waitcnt lgkmcnt(0)
	v_writelane_b32 v253, s8, 0
	s_nop 1
	v_writelane_b32 v253, s9, 1
	v_writelane_b32 v253, s10, 2
	v_writelane_b32 v253, s11, 3
	v_writelane_b32 v253, s12, 4
	v_writelane_b32 v253, s13, 5
	v_writelane_b32 v253, s14, 6
	v_writelane_b32 v253, s15, 7
	v_writelane_b32 v253, s16, 8
	v_writelane_b32 v253, s17, 9
	v_writelane_b32 v253, s18, 10
	v_writelane_b32 v253, s19, 11
	v_writelane_b32 v253, s20, 12
	v_writelane_b32 v253, s21, 13
	v_writelane_b32 v253, s22, 14
	v_writelane_b32 v253, s23, 15
	v_writelane_b32 v253, s3, 16
	s_mov_b64 s[8:9], s[92:93]
	v_writelane_b32 v253, s88, 17
	s_mov_b32 s10, s2
	s_nop 0
	v_writelane_b32 v253, s89, 18
	v_writelane_b32 v253, s90, 19
	v_writelane_b32 v253, s91, 20
	v_writelane_b32 v253, s92, 21
	v_writelane_b32 v253, s93, 22
	v_writelane_b32 v253, s94, 23
	v_writelane_b32 v253, s95, 24
	v_writelane_b32 v253, s52, 25
	v_readfirstlane_b32 s8, v2
	s_ashr_i32 s10, s8, 6
	v_writelane_b32 v253, s53, 26
	v_writelane_b32 v253, s54, 27
	v_writelane_b32 v253, s55, 28
	v_writelane_b32 v253, s56, 29
	v_writelane_b32 v253, s57, 30
	v_writelane_b32 v253, s58, 31
	v_writelane_b32 v253, s59, 32
	v_writelane_b32 v253, s60, 33
	v_writelane_b32 v253, s61, 34
	v_writelane_b32 v253, s62, 35
	v_writelane_b32 v253, s63, 36
	v_writelane_b32 v253, s64, 37
	v_writelane_b32 v253, s65, 38
	v_writelane_b32 v253, s66, 39
	s_add_i32 s11, s10, s3
	v_writelane_b32 v253, s67, 40
	s_cmp_gt_i32 s11, 0x161ff
	v_writelane_b32 v253, s29, 41
	s_cbranch_scc1 .LBB0_49
	s_lshl_b32 s8, s10, 14
	s_add_u32 s87, s0, 0x16400000
	s_addc_u32 s88, s1, 0
	s_add_u32 s90, s0, 0x15400000
	s_addc_u32 s91, s1, 0
	s_add_u32 s92, s0, 0x14000000
	s_addc_u32 s21, s1, 0
	s_add_u32 s22, s0, 0x11000000
	s_addc_u32 s23, s1, 0
	s_add_u32 s24, s0, 0x9000000
	v_and_b32_e32 v4, 31, v2
	s_addc_u32 s25, s1, 0
	v_bfe_u32 v1, v2, 5, 1
	v_lshl_or_b32 v3, v4, 2, s8
	s_movk_i32 s9, 0x84
	v_and_b32_e32 v5, 7, v2
	v_bfe_u32 v25, v2, 3, 3
	s_add_u32 s26, s0, 0x1000000
	v_readlane_b32 s60, v253, 0
	v_mov_b32_e32 v11, 0
	v_mad_u32_u24 v24, v1, s9, v3
	v_mul_u32_u24_e32 v2, 0x420, v5
	v_lshlrev_b32_e32 v3, 2, v25
	s_addc_u32 s27, s1, 0
	v_lshlrev_b32_e32 v10, 4, v5
	v_readlane_b32 s64, v253, 4
	v_readlane_b32 s65, v253, 5
	v_or3_b32 v26, s8, v2, v3
	v_lshl_add_u64 v[2:3], s[0:1], 0, v[10:11]
	s_mov_b64 s[0:1], 0x15000000
	s_cmp_lg_u64 s[64:65], 0
	v_lshl_add_u64 v[12:13], v[2:3], 0, s[0:1]
	s_cselect_b64 s[0:1], -1, 0
	s_cmp_lg_u64 s[56:57], 0
	v_lshlrev_b32_e32 v6, 3, v5
	v_lshlrev_b32_e32 v10, 5, v5
	v_readlane_b32 s61, v253, 1
	v_readlane_b32 s62, v253, 2
	v_readlane_b32 s63, v253, 3
	v_readlane_b32 s66, v253, 6
	v_readlane_b32 s67, v253, 7
	v_readlane_b32 s68, v253, 8
	v_readlane_b32 s69, v253, 9
	v_readlane_b32 s70, v253, 10
	v_readlane_b32 s71, v253, 11
	v_readlane_b32 s72, v253, 12
	v_readlane_b32 s73, v253, 13
	v_readlane_b32 s74, v253, 14
	v_readlane_b32 s75, v253, 15
	v_writelane_b32 v253, s0, 42
	s_cselect_b64 s[8:9], -1, 0
	s_add_i32 s28, s11, 0xfffeae00
	s_lshl_b32 s11, s29, 6
	s_lshl_b32 s10, s10, 3
	v_or_b32_e32 v27, 8, v25
	v_or_b32_e32 v28, 16, v25
	v_or_b32_e32 v29, 24, v25
	v_lshl_add_u64 v[14:15], s[64:65], 0, v[10:11]
	v_writelane_b32 v253, s1, 43
	s_add_i32 s29, s11, s10
	s_lshl_b32 s30, s96, 6
	s_movk_i32 s31, 0x4000
	s_mov_b32 s34, 0x8000
	s_mov_b32 s35, 0xc000
	s_mov_b32 s36, 0x10000
	s_mov_b32 s37, 0x14000
	s_mov_b32 s38, 0x18000
	s_mov_b32 s39, 0x1c000
	s_mov_b32 s40, 0x20000
	s_mov_b32 s41, 0x24000
	s_mov_b32 s42, 0x28000
	s_mov_b32 s43, 0x2c000
	s_mov_b32 s44, 0x30000
	s_mov_b32 s45, 0x34000
	s_mov_b32 s46, 0x38000
	s_mov_b32 s47, 0x3c000
	s_mov_b32 s48, 0x40000
	s_mov_b32 s49, 0x44000
	s_mov_b32 s51, 0x48000
	s_mov_b32 s52, 0x4c000
	s_mov_b32 s53, 0x50000
	s_mov_b32 s54, 0x54000
	s_mov_b32 s55, 0x58000
	s_mov_b32 s56, 0x5c000
	s_mov_b32 s57, 0x60000
	s_mov_b32 s58, 0x64000
	s_mov_b32 s59, 0x68000
	s_mov_b32 s60, 0x6c000
	s_mov_b32 s61, 0x70000
	s_mov_b32 s62, 0x74000
	s_mov_b32 s63, 0x78000
	s_mov_b32 s3, 0x7c000
	s_movk_i32 s89, 0x1000
	s_movk_i32 s93, 0x2000
	s_movk_i32 s94, 0x7000
	s_mov_b32 s95, 0x9000
	s_mov_b32 s16, 0xa000
	s_mov_b32 s17, 0xb000
	s_mov_b32 s18, 0xd000
	s_mov_b32 s19, 0xe000
	v_lshlrev_b32_e32 v16, 2, v4
	v_add_u32_e32 v30, 0x400, v24
	v_add_u32_e32 v31, 0x800, v24
	v_add_u32_e32 v32, 0xc00, v24
	v_add_u32_e32 v33, 0x1000, v24
	v_add_u32_e32 v34, 0x1400, v24
	v_add_u32_e32 v35, 0x1800, v24
	v_add_u32_e32 v36, 0x1c00, v24
	v_lshlrev_b32_e32 v18, 1, v6
	v_lshlrev_b32_e32 v20, 2, v6
	s_mov_b32 s0, 0x90000
	s_mov_b32 s1, 0xc0000
	s_mov_b32 s20, 0xf0000
	s_mov_b32 s80, 0x120000
	s_mov_b32 s81, 0x150000
	s_mov_b32 s11, 0
	s_cmp_lg_u32 s96, 0x100
	s_cbranch_scc1 .Lmy_cv_skip
	s_add_i32 s76, s28, 0x15200
	v_lshlrev_b32_e32 v180, 15, v1
	v_or_b32_e32 v180, v180, v16
	v_or_b32_e32 v181, 0, v25
	v_lshlrev_b32_e32 v181, 12, v181
	v_or_b32_e32 v181, v181, v18
	v_or_b32_e32 v182, 8, v25
	v_lshlrev_b32_e32 v182, 12, v182
	v_or_b32_e32 v182, v182, v18
	v_or_b32_e32 v183, 16, v25
	v_lshlrev_b32_e32 v183, 12, v183
	v_or_b32_e32 v183, v183, v18
	v_or_b32_e32 v184, 24, v25
	v_lshlrev_b32_e32 v184, 12, v184
	v_or_b32_e32 v184, v184, v18
	v_readlane_b32 s64, v253, 31
	v_readlane_b32 s65, v253, 32
	v_readlane_b32 s68, v253, 29
	v_readlane_b32 s69, v253, 30
	s_lshr_b32 s77, s76, 8
	s_and_b32 s78, s76, 0xff
	s_lshl_b32 s79, s77, 21
	s_add_u32 s64, s64, s79
	s_addc_u32 s65, s65, 0
	s_lshl_b32 s79, s78, 7
	s_add_u32 s64, s64, s79
	s_addc_u32 s65, s65, 0
	s_lshl_b32 s79, s77, 8
	s_add_u32 s68, s68, s79
	s_addc_u32 s69, s69, 0
	s_lshl_b32 s79, s78, 17
	s_add_u32 s66, s26, s79
	s_addc_u32 s67, s27, 0
	s_lshl_b32 s79, s77, 7
	s_add_u32 s66, s66, s79
	s_addc_u32 s67, s67, 0
	s_mov_b32 s78, 12
	s_mov_b32 s70, 0
	s_mov_b64 s[72:73], s[64:65]
	global_load_dword v100, v180, s[72:73]
	s_add_u32 s72, s72, 0x10000
	s_addc_u32 s73, s73, 0
	global_load_dword v101, v180, s[72:73]
	s_add_u32 s72, s72, 0x10000
	s_addc_u32 s73, s73, 0
	global_load_dword v102, v180, s[72:73]
	s_add_u32 s72, s72, 0x10000
	s_addc_u32 s73, s73, 0
	global_load_dword v103, v180, s[72:73]
	s_add_u32 s72, s72, 0x10000
	s_addc_u32 s73, s73, 0
	global_load_dword v104, v180, s[72:73]
	s_add_u32 s72, s72, 0x10000
	s_addc_u32 s73, s73, 0
	global_load_dword v105, v180, s[72:73]
	s_add_u32 s72, s72, 0x10000
	s_addc_u32 s73, s73, 0
	global_load_dword v106, v180, s[72:73]
	s_add_u32 s72, s72, 0x10000
	s_addc_u32 s73, s73, 0
	global_load_dword v107, v180, s[72:73]
	s_add_u32 s72, s72, 0x10000
	s_addc_u32 s73, s73, 0
	global_load_dword v108, v180, s[72:73]
	s_add_u32 s72, s72, 0x10000
	s_addc_u32 s73, s73, 0
	global_load_dword v109, v180, s[72:73]
	s_add_u32 s72, s72, 0x10000
	s_addc_u32 s73, s73, 0
	global_load_dword v110, v180, s[72:73]
	s_add_u32 s72, s72, 0x10000
	s_addc_u32 s73, s73, 0
	global_load_dword v111, v180, s[72:73]
	s_add_u32 s72, s72, 0x10000
	s_addc_u32 s73, s73, 0
	global_load_dword v112, v180, s[72:73]
	s_add_u32 s72, s72, 0x10000
	s_addc_u32 s73, s73, 0
	global_load_dword v113, v180, s[72:73]
	s_add_u32 s72, s72, 0x10000
	s_addc_u32 s73, s73, 0
	global_load_dword v114, v180, s[72:73]
	s_add_u32 s72, s72, 0x10000
	s_addc_u32 s73, s73, 0
	global_load_dword v115, v180, s[72:73]
	s_add_u32 s72, s72, 0x10000
	s_addc_u32 s73, s73, 0
	global_load_dword v116, v180, s[72:73]
	s_add_u32 s72, s72, 0x10000
	s_addc_u32 s73, s73, 0
	global_load_dword v117, v180, s[72:73]
	s_add_u32 s72, s72, 0x10000
	s_addc_u32 s73, s73, 0
	global_load_dword v118, v180, s[72:73]
	s_add_u32 s72, s72, 0x10000
	s_addc_u32 s73, s73, 0
	global_load_dword v119, v180, s[72:73]
	s_add_u32 s72, s72, 0x10000
	s_addc_u32 s73, s73, 0
	global_load_dword v120, v180, s[72:73]
	s_add_u32 s72, s72, 0x10000
	s_addc_u32 s73, s73, 0
	global_load_dword v121, v180, s[72:73]
	s_add_u32 s72, s72, 0x10000
	s_addc_u32 s73, s73, 0
	global_load_dword v122, v180, s[72:73]
	s_add_u32 s72, s72, 0x10000
	s_addc_u32 s73, s73, 0
	global_load_dword v123, v180, s[72:73]
	s_add_u32 s72, s72, 0x10000
	s_addc_u32 s73, s73, 0
	global_load_dword v124, v180, s[72:73]
	s_add_u32 s72, s72, 0x10000
	s_addc_u32 s73, s73, 0
	global_load_dword v125, v180, s[72:73]
	s_add_u32 s72, s72, 0x10000
	s_addc_u32 s73, s73, 0
	global_load_dword v126, v180, s[72:73]
	s_add_u32 s72, s72, 0x10000
	s_addc_u32 s73, s73, 0
	global_load_dword v127, v180, s[72:73]
	s_add_u32 s72, s72, 0x10000
	s_addc_u32 s73, s73, 0
	global_load_dword v128, v180, s[72:73]
	s_add_u32 s72, s72, 0x10000
	s_addc_u32 s73, s73, 0
	global_load_dword v129, v180, s[72:73]
	s_add_u32 s72, s72, 0x10000
	s_addc_u32 s73, s73, 0
	global_load_dword v130, v180, s[72:73]
	s_add_u32 s72, s72, 0x10000
	s_addc_u32 s73, s73, 0
	global_load_dword v131, v180, s[72:73]
	global_load_dwordx4 v[132:135], v20, s[68:69]
	global_load_dwordx4 v[136:139], v20, s[68:69] offset:16
	s_add_u32 s64, s64, 0x1000000
	s_addc_u32 s65, s65, 0
	s_add_u32 s68, s68, 0x800
	s_addc_u32 s69, s69, 0
.Lmy_cvw1_loop:
	s_add_i32 s71, s70, 1
	s_cmp_lt_u32 s71, s78
	s_cbranch_scc0 .Lmy_cvw1_elast
	s_mov_b64 s[72:73], s[64:65]
	global_load_dword v140, v180, s[72:73]
	s_add_u32 s72, s72, 0x10000
	s_addc_u32 s73, s73, 0
	global_load_dword v141, v180, s[72:73]
	s_add_u32 s72, s72, 0x10000
	s_addc_u32 s73, s73, 0
	global_load_dword v142, v180, s[72:73]
	s_add_u32 s72, s72, 0x10000
	s_addc_u32 s73, s73, 0
	global_load_dword v143, v180, s[72:73]
	s_add_u32 s72, s72, 0x10000
	s_addc_u32 s73, s73, 0
	global_load_dword v144, v180, s[72:73]
	s_add_u32 s72, s72, 0x10000
	s_addc_u32 s73, s73, 0
	global_load_dword v145, v180, s[72:73]
	s_add_u32 s72, s72, 0x10000
	s_addc_u32 s73, s73, 0
	global_load_dword v146, v180, s[72:73]
	s_add_u32 s72, s72, 0x10000
	s_addc_u32 s73, s73, 0
	global_load_dword v147, v180, s[72:73]
	s_add_u32 s72, s72, 0x10000
	s_addc_u32 s73, s73, 0
	global_load_dword v148, v180, s[72:73]
	s_add_u32 s72, s72, 0x10000
	s_addc_u32 s73, s73, 0
	global_load_dword v149, v180, s[72:73]
	s_add_u32 s72, s72, 0x10000
	s_addc_u32 s73, s73, 0
	global_load_dword v150, v180, s[72:73]
	s_add_u32 s72, s72, 0x10000
	s_addc_u32 s73, s73, 0
	global_load_dword v151, v180, s[72:73]
	s_add_u32 s72, s72, 0x10000
	s_addc_u32 s73, s73, 0
	global_load_dword v152, v180, s[72:73]
	s_add_u32 s72, s72, 0x10000
	s_addc_u32 s73, s73, 0
	global_load_dword v153, v180, s[72:73]
	s_add_u32 s72, s72, 0x10000
	s_addc_u32 s73, s73, 0
	global_load_dword v154, v180, s[72:73]
	s_add_u32 s72, s72, 0x10000
	s_addc_u32 s73, s73, 0
	global_load_dword v155, v180, s[72:73]
	s_add_u32 s72, s72, 0x10000
	s_addc_u32 s73, s73, 0
	global_load_dword v156, v180, s[72:73]
	s_add_u32 s72, s72, 0x10000
	s_addc_u32 s73, s73, 0
	global_load_dword v157, v180, s[72:73]
	s_add_u32 s72, s72, 0x10000
	s_addc_u32 s73, s73, 0
	global_load_dword v158, v180, s[72:73]
	s_add_u32 s72, s72, 0x10000
	s_addc_u32 s73, s73, 0
	global_load_dword v159, v180, s[72:73]
	s_add_u32 s72, s72, 0x10000
	s_addc_u32 s73, s73, 0
	global_load_dword v160, v180, s[72:73]
	s_add_u32 s72, s72, 0x10000
	s_addc_u32 s73, s73, 0
	global_load_dword v161, v180, s[72:73]
	s_add_u32 s72, s72, 0x10000
	s_addc_u32 s73, s73, 0
	global_load_dword v162, v180, s[72:73]
	s_add_u32 s72, s72, 0x10000
	s_addc_u32 s73, s73, 0
	global_load_dword v163, v180, s[72:73]
	s_add_u32 s72, s72, 0x10000
	s_addc_u32 s73, s73, 0
	global_load_dword v164, v180, s[72:73]
	s_add_u32 s72, s72, 0x10000
	s_addc_u32 s73, s73, 0
	global_load_dword v165, v180, s[72:73]
	s_add_u32 s72, s72, 0x10000
	s_addc_u32 s73, s73, 0
	global_load_dword v166, v180, s[72:73]
	s_add_u32 s72, s72, 0x10000
	s_addc_u32 s73, s73, 0
	global_load_dword v167, v180, s[72:73]
	s_add_u32 s72, s72, 0x10000
	s_addc_u32 s73, s73, 0
	global_load_dword v168, v180, s[72:73]
	s_add_u32 s72, s72, 0x10000
	s_addc_u32 s73, s73, 0
	global_load_dword v169, v180, s[72:73]
	s_add_u32 s72, s72, 0x10000
	s_addc_u32 s73, s73, 0
	global_load_dword v170, v180, s[72:73]
	s_add_u32 s72, s72, 0x10000
	s_addc_u32 s73, s73, 0
	global_load_dword v171, v180, s[72:73]
	global_load_dwordx4 v[172:175], v20, s[68:69]
	global_load_dwordx4 v[176:179], v20, s[68:69] offset:16
	s_add_u32 s64, s64, 0x1000000
	s_addc_u32 s65, s65, 0
	s_add_u32 s68, s68, 0x800
	s_addc_u32 s69, s69, 0
	s_waitcnt vmcnt(34)
	ds_write2_b32 v24, v100, v101 offset1:66
	ds_write2_b32 v24, v102, v103 offset0:132 offset1:198
	ds_write2_b32 v30, v104, v105 offset0:8 offset1:74
	ds_write2_b32 v30, v106, v107 offset0:140 offset1:206
	ds_write2_b32 v31, v108, v109 offset0:16 offset1:82
	ds_write2_b32 v31, v110, v111 offset0:148 offset1:214
	ds_write2_b32 v32, v112, v113 offset0:24 offset1:90
	ds_write2_b32 v32, v114, v115 offset0:156 offset1:222
	ds_write2_b32 v33, v116, v117 offset0:32 offset1:98
	ds_write2_b32 v33, v118, v119 offset0:164 offset1:230
	ds_write2_b32 v34, v120, v121 offset0:40 offset1:106
	ds_write2_b32 v34, v122, v123 offset0:172 offset1:238
	ds_write2_b32 v35, v124, v125 offset0:48 offset1:114
	ds_write2_b32 v35, v126, v127 offset0:180 offset1:246
	ds_write2_b32 v36, v128, v129 offset0:56 offset1:122
	ds_write2_b32 v36, v130, v131 offset0:188 offset1:254
	s_waitcnt lgkmcnt(0)
	ds_read_b32 v76, v26
	ds_read_b32 v77, v26 offset:132
	ds_read_b32 v78, v26 offset:264
	ds_read_b32 v79, v26 offset:396
	ds_read_b32 v80, v26 offset:528
	ds_read_b32 v81, v26 offset:660
	ds_read_b32 v82, v26 offset:792
	ds_read_b32 v83, v26 offset:924
	s_waitcnt lgkmcnt(0)
	v_pk_mul_f32 v[76:77], v[132:133], v[76:77]
	v_pk_mul_f32 v[78:79], v[134:135], v[78:79]
	v_pk_mul_f32 v[80:81], v[136:137], v[80:81]
	v_pk_mul_f32 v[82:83], v[138:139], v[82:83]
	v_cvt_pk_bf16_f32 v60, v76, v77
	v_cvt_pk_bf16_f32 v61, v78, v79
	v_cvt_pk_bf16_f32 v62, v80, v81
	v_cvt_pk_bf16_f32 v63, v82, v83
	global_store_dwordx4 v181, v[60:63], s[66:67]
	ds_read_b32 v76, v26 offset:32
	ds_read_b32 v77, v26 offset:164
	ds_read_b32 v78, v26 offset:296
	ds_read_b32 v79, v26 offset:428
	ds_read_b32 v80, v26 offset:560
	ds_read_b32 v81, v26 offset:692
	ds_read_b32 v82, v26 offset:824
	ds_read_b32 v83, v26 offset:956
	s_waitcnt lgkmcnt(0)
	v_pk_mul_f32 v[76:77], v[132:133], v[76:77]
	v_pk_mul_f32 v[78:79], v[134:135], v[78:79]
	v_pk_mul_f32 v[80:81], v[136:137], v[80:81]
	v_pk_mul_f32 v[82:83], v[138:139], v[82:83]
	v_cvt_pk_bf16_f32 v64, v76, v77
	v_cvt_pk_bf16_f32 v65, v78, v79
	v_cvt_pk_bf16_f32 v66, v80, v81
	v_cvt_pk_bf16_f32 v67, v82, v83
	global_store_dwordx4 v182, v[64:67], s[66:67]
	ds_read_b32 v76, v26 offset:64
	ds_read_b32 v77, v26 offset:196
	ds_read_b32 v78, v26 offset:328
	ds_read_b32 v79, v26 offset:460
	ds_read_b32 v80, v26 offset:592
	ds_read_b32 v81, v26 offset:724
	ds_read_b32 v82, v26 offset:856
	ds_read_b32 v83, v26 offset:988
	s_waitcnt lgkmcnt(0)
	v_pk_mul_f32 v[76:77], v[132:133], v[76:77]
	v_pk_mul_f32 v[78:79], v[134:135], v[78:79]
	v_pk_mul_f32 v[80:81], v[136:137], v[80:81]
	v_pk_mul_f32 v[82:83], v[138:139], v[82:83]
	v_cvt_pk_bf16_f32 v68, v76, v77
	v_cvt_pk_bf16_f32 v69, v78, v79
	v_cvt_pk_bf16_f32 v70, v80, v81
	v_cvt_pk_bf16_f32 v71, v82, v83
	global_store_dwordx4 v183, v[68:71], s[66:67]
	ds_read_b32 v76, v26 offset:96
	ds_read_b32 v77, v26 offset:228
	ds_read_b32 v78, v26 offset:360
	ds_read_b32 v79, v26 offset:492
	ds_read_b32 v80, v26 offset:624
	ds_read_b32 v81, v26 offset:756
	ds_read_b32 v82, v26 offset:888
	ds_read_b32 v83, v26 offset:1020
	s_waitcnt lgkmcnt(0)
	v_pk_mul_f32 v[76:77], v[132:133], v[76:77]
	v_pk_mul_f32 v[78:79], v[134:135], v[78:79]
	v_pk_mul_f32 v[80:81], v[136:137], v[80:81]
	v_pk_mul_f32 v[82:83], v[138:139], v[82:83]
	v_cvt_pk_bf16_f32 v72, v76, v77
	v_cvt_pk_bf16_f32 v73, v78, v79
	v_cvt_pk_bf16_f32 v74, v80, v81
	v_cvt_pk_bf16_f32 v75, v82, v83
	global_store_dwordx4 v184, v[72:75], s[66:67]
	s_add_i32 s70, s70, 1
	s_and_b32 s71, s70, 3
	s_cmp_eq_u32 s71, 0
	s_mov_b32 s79, 0x400
	s_cselect_b32 s71, 0x1fff400, s79
	s_add_u32 s66, s66, s71
	s_addc_u32 s67, s67, 0
	s_add_i32 s71, s70, 1
	s_cmp_lt_u32 s71, s78
	s_cbranch_scc0 .Lmy_cvw1_olast
	s_mov_b64 s[72:73], s[64:65]
	global_load_dword v100, v180, s[72:73]
	s_add_u32 s72, s72, 0x10000
	s_addc_u32 s73, s73, 0
	global_load_dword v101, v180, s[72:73]
	s_add_u32 s72, s72, 0x10000
	s_addc_u32 s73, s73, 0
	global_load_dword v102, v180, s[72:73]
	s_add_u32 s72, s72, 0x10000
	s_addc_u32 s73, s73, 0
	global_load_dword v103, v180, s[72:73]
	s_add_u32 s72, s72, 0x10000
	s_addc_u32 s73, s73, 0
	global_load_dword v104, v180, s[72:73]
	s_add_u32 s72, s72, 0x10000
	s_addc_u32 s73, s73, 0
	global_load_dword v105, v180, s[72:73]
	s_add_u32 s72, s72, 0x10000
	s_addc_u32 s73, s73, 0
	global_load_dword v106, v180, s[72:73]
	s_add_u32 s72, s72, 0x10000
	s_addc_u32 s73, s73, 0
	global_load_dword v107, v180, s[72:73]
	s_add_u32 s72, s72, 0x10000
	s_addc_u32 s73, s73, 0
	global_load_dword v108, v180, s[72:73]
	s_add_u32 s72, s72, 0x10000
	s_addc_u32 s73, s73, 0
	global_load_dword v109, v180, s[72:73]
	s_add_u32 s72, s72, 0x10000
	s_addc_u32 s73, s73, 0
	global_load_dword v110, v180, s[72:73]
	s_add_u32 s72, s72, 0x10000
	s_addc_u32 s73, s73, 0
	global_load_dword v111, v180, s[72:73]
	s_add_u32 s72, s72, 0x10000
	s_addc_u32 s73, s73, 0
	global_load_dword v112, v180, s[72:73]
	s_add_u32 s72, s72, 0x10000
	s_addc_u32 s73, s73, 0
	global_load_dword v113, v180, s[72:73]
	s_add_u32 s72, s72, 0x10000
	s_addc_u32 s73, s73, 0
	global_load_dword v114, v180, s[72:73]
	s_add_u32 s72, s72, 0x10000
	s_addc_u32 s73, s73, 0
	global_load_dword v115, v180, s[72:73]
	s_add_u32 s72, s72, 0x10000
	s_addc_u32 s73, s73, 0
	global_load_dword v116, v180, s[72:73]
	s_add_u32 s72, s72, 0x10000
	s_addc_u32 s73, s73, 0
	global_load_dword v117, v180, s[72:73]
	s_add_u32 s72, s72, 0x10000
	s_addc_u32 s73, s73, 0
	global_load_dword v118, v180, s[72:73]
	s_add_u32 s72, s72, 0x10000
	s_addc_u32 s73, s73, 0
	global_load_dword v119, v180, s[72:73]
	s_add_u32 s72, s72, 0x10000
	s_addc_u32 s73, s73, 0
	global_load_dword v120, v180, s[72:73]
	s_add_u32 s72, s72, 0x10000
	s_addc_u32 s73, s73, 0
	global_load_dword v121, v180, s[72:73]
	s_add_u32 s72, s72, 0x10000
	s_addc_u32 s73, s73, 0
	global_load_dword v122, v180, s[72:73]
	s_add_u32 s72, s72, 0x10000
	s_addc_u32 s73, s73, 0
	global_load_dword v123, v180, s[72:73]
	s_add_u32 s72, s72, 0x10000
	s_addc_u32 s73, s73, 0
	global_load_dword v124, v180, s[72:73]
	s_add_u32 s72, s72, 0x10000
	s_addc_u32 s73, s73, 0
	global_load_dword v125, v180, s[72:73]
	s_add_u32 s72, s72, 0x10000
	s_addc_u32 s73, s73, 0
	global_load_dword v126, v180, s[72:73]
	s_add_u32 s72, s72, 0x10000
	s_addc_u32 s73, s73, 0
	global_load_dword v127, v180, s[72:73]
	s_add_u32 s72, s72, 0x10000
	s_addc_u32 s73, s73, 0
	global_load_dword v128, v180, s[72:73]
	s_add_u32 s72, s72, 0x10000
	s_addc_u32 s73, s73, 0
	global_load_dword v129, v180, s[72:73]
	s_add_u32 s72, s72, 0x10000
	s_addc_u32 s73, s73, 0
	global_load_dword v130, v180, s[72:73]
	s_add_u32 s72, s72, 0x10000
	s_addc_u32 s73, s73, 0
	global_load_dword v131, v180, s[72:73]
	global_load_dwordx4 v[132:135], v20, s[68:69]
	global_load_dwordx4 v[136:139], v20, s[68:69] offset:16
	s_add_u32 s64, s64, 0x1000000
	s_addc_u32 s65, s65, 0
	s_add_u32 s68, s68, 0x800
	s_addc_u32 s69, s69, 0
	s_waitcnt vmcnt(34)
	ds_write2_b32 v24, v140, v141 offset1:66
	ds_write2_b32 v24, v142, v143 offset0:132 offset1:198
	ds_write2_b32 v30, v144, v145 offset0:8 offset1:74
	ds_write2_b32 v30, v146, v147 offset0:140 offset1:206
	ds_write2_b32 v31, v148, v149 offset0:16 offset1:82
	ds_write2_b32 v31, v150, v151 offset0:148 offset1:214
	ds_write2_b32 v32, v152, v153 offset0:24 offset1:90
	ds_write2_b32 v32, v154, v155 offset0:156 offset1:222
	ds_write2_b32 v33, v156, v157 offset0:32 offset1:98
	ds_write2_b32 v33, v158, v159 offset0:164 offset1:230
	ds_write2_b32 v34, v160, v161 offset0:40 offset1:106
	ds_write2_b32 v34, v162, v163 offset0:172 offset1:238
	ds_write2_b32 v35, v164, v165 offset0:48 offset1:114
	ds_write2_b32 v35, v166, v167 offset0:180 offset1:246
	ds_write2_b32 v36, v168, v169 offset0:56 offset1:122
	ds_write2_b32 v36, v170, v171 offset0:188 offset1:254
	s_waitcnt lgkmcnt(0)
	ds_read_b32 v76, v26
	ds_read_b32 v77, v26 offset:132
	ds_read_b32 v78, v26 offset:264
	ds_read_b32 v79, v26 offset:396
	ds_read_b32 v80, v26 offset:528
	ds_read_b32 v81, v26 offset:660
	ds_read_b32 v82, v26 offset:792
	ds_read_b32 v83, v26 offset:924
	s_waitcnt lgkmcnt(0)
	v_pk_mul_f32 v[76:77], v[172:173], v[76:77]
	v_pk_mul_f32 v[78:79], v[174:175], v[78:79]
	v_pk_mul_f32 v[80:81], v[176:177], v[80:81]
	v_pk_mul_f32 v[82:83], v[178:179], v[82:83]
	v_cvt_pk_bf16_f32 v60, v76, v77
	v_cvt_pk_bf16_f32 v61, v78, v79
	v_cvt_pk_bf16_f32 v62, v80, v81
	v_cvt_pk_bf16_f32 v63, v82, v83
	global_store_dwordx4 v181, v[60:63], s[66:67]
	ds_read_b32 v76, v26 offset:32
	ds_read_b32 v77, v26 offset:164
	ds_read_b32 v78, v26 offset:296
	ds_read_b32 v79, v26 offset:428
	ds_read_b32 v80, v26 offset:560
	ds_read_b32 v81, v26 offset:692
	ds_read_b32 v82, v26 offset:824
	ds_read_b32 v83, v26 offset:956
	s_waitcnt lgkmcnt(0)
	v_pk_mul_f32 v[76:77], v[172:173], v[76:77]
	v_pk_mul_f32 v[78:79], v[174:175], v[78:79]
	v_pk_mul_f32 v[80:81], v[176:177], v[80:81]
	v_pk_mul_f32 v[82:83], v[178:179], v[82:83]
	v_cvt_pk_bf16_f32 v64, v76, v77
	v_cvt_pk_bf16_f32 v65, v78, v79
	v_cvt_pk_bf16_f32 v66, v80, v81
	v_cvt_pk_bf16_f32 v67, v82, v83
	global_store_dwordx4 v182, v[64:67], s[66:67]
	ds_read_b32 v76, v26 offset:64
	ds_read_b32 v77, v26 offset:196
	ds_read_b32 v78, v26 offset:328
	ds_read_b32 v79, v26 offset:460
	ds_read_b32 v80, v26 offset:592
	ds_read_b32 v81, v26 offset:724
	ds_read_b32 v82, v26 offset:856
	ds_read_b32 v83, v26 offset:988
	s_waitcnt lgkmcnt(0)
	v_pk_mul_f32 v[76:77], v[172:173], v[76:77]
	v_pk_mul_f32 v[78:79], v[174:175], v[78:79]
	v_pk_mul_f32 v[80:81], v[176:177], v[80:81]
	v_pk_mul_f32 v[82:83], v[178:179], v[82:83]
	v_cvt_pk_bf16_f32 v68, v76, v77
	v_cvt_pk_bf16_f32 v69, v78, v79
	v_cvt_pk_bf16_f32 v70, v80, v81
	v_cvt_pk_bf16_f32 v71, v82, v83
	global_store_dwordx4 v183, v[68:71], s[66:67]
	ds_read_b32 v76, v26 offset:96
	ds_read_b32 v77, v26 offset:228
	ds_read_b32 v78, v26 offset:360
	ds_read_b32 v79, v26 offset:492
	ds_read_b32 v80, v26 offset:624
	ds_read_b32 v81, v26 offset:756
	ds_read_b32 v82, v26 offset:888
	ds_read_b32 v83, v26 offset:1020
	s_waitcnt lgkmcnt(0)
	v_pk_mul_f32 v[76:77], v[172:173], v[76:77]
	v_pk_mul_f32 v[78:79], v[174:175], v[78:79]
	v_pk_mul_f32 v[80:81], v[176:177], v[80:81]
	v_pk_mul_f32 v[82:83], v[178:179], v[82:83]
	v_cvt_pk_bf16_f32 v72, v76, v77
	v_cvt_pk_bf16_f32 v73, v78, v79
	v_cvt_pk_bf16_f32 v74, v80, v81
	v_cvt_pk_bf16_f32 v75, v82, v83
	global_store_dwordx4 v184, v[72:75], s[66:67]
	s_add_i32 s70, s70, 1
	s_and_b32 s71, s70, 3
	s_cmp_eq_u32 s71, 0
	s_mov_b32 s79, 0x400
	s_cselect_b32 s71, 0x1fff400, s79
	s_add_u32 s66, s66, s71
	s_addc_u32 s67, s67, 0
	s_branch .Lmy_cvw1_loop
.Lmy_cvw1_elast:
	s_waitcnt vmcnt(0)
	ds_write2_b32 v24, v100, v101 offset1:66
	ds_write2_b32 v24, v102, v103 offset0:132 offset1:198
	ds_write2_b32 v30, v104, v105 offset0:8 offset1:74
	ds_write2_b32 v30, v106, v107 offset0:140 offset1:206
	ds_write2_b32 v31, v108, v109 offset0:16 offset1:82
	ds_write2_b32 v31, v110, v111 offset0:148 offset1:214
	ds_write2_b32 v32, v112, v113 offset0:24 offset1:90
	ds_write2_b32 v32, v114, v115 offset0:156 offset1:222
	ds_write2_b32 v33, v116, v117 offset0:32 offset1:98
	ds_write2_b32 v33, v118, v119 offset0:164 offset1:230
	ds_write2_b32 v34, v120, v121 offset0:40 offset1:106
	ds_write2_b32 v34, v122, v123 offset0:172 offset1:238
	ds_write2_b32 v35, v124, v125 offset0:48 offset1:114
	ds_write2_b32 v35, v126, v127 offset0:180 offset1:246
	ds_write2_b32 v36, v128, v129 offset0:56 offset1:122
	ds_write2_b32 v36, v130, v131 offset0:188 offset1:254
	s_waitcnt lgkmcnt(0)
	ds_read_b32 v76, v26
	ds_read_b32 v77, v26 offset:132
	ds_read_b32 v78, v26 offset:264
	ds_read_b32 v79, v26 offset:396
	ds_read_b32 v80, v26 offset:528
	ds_read_b32 v81, v26 offset:660
	ds_read_b32 v82, v26 offset:792
	ds_read_b32 v83, v26 offset:924
	s_waitcnt lgkmcnt(0)
	v_pk_mul_f32 v[76:77], v[132:133], v[76:77]
	v_pk_mul_f32 v[78:79], v[134:135], v[78:79]
	v_pk_mul_f32 v[80:81], v[136:137], v[80:81]
	v_pk_mul_f32 v[82:83], v[138:139], v[82:83]
	v_cvt_pk_bf16_f32 v60, v76, v77
	v_cvt_pk_bf16_f32 v61, v78, v79
	v_cvt_pk_bf16_f32 v62, v80, v81
	v_cvt_pk_bf16_f32 v63, v82, v83
	global_store_dwordx4 v181, v[60:63], s[66:67]
	ds_read_b32 v76, v26 offset:32
	ds_read_b32 v77, v26 offset:164
	ds_read_b32 v78, v26 offset:296
	ds_read_b32 v79, v26 offset:428
	ds_read_b32 v80, v26 offset:560
	ds_read_b32 v81, v26 offset:692
	ds_read_b32 v82, v26 offset:824
	ds_read_b32 v83, v26 offset:956
	s_waitcnt lgkmcnt(0)
	v_pk_mul_f32 v[76:77], v[132:133], v[76:77]
	v_pk_mul_f32 v[78:79], v[134:135], v[78:79]
	v_pk_mul_f32 v[80:81], v[136:137], v[80:81]
	v_pk_mul_f32 v[82:83], v[138:139], v[82:83]
	v_cvt_pk_bf16_f32 v64, v76, v77
	v_cvt_pk_bf16_f32 v65, v78, v79
	v_cvt_pk_bf16_f32 v66, v80, v81
	v_cvt_pk_bf16_f32 v67, v82, v83
	global_store_dwordx4 v182, v[64:67], s[66:67]
	ds_read_b32 v76, v26 offset:64
	ds_read_b32 v77, v26 offset:196
	ds_read_b32 v78, v26 offset:328
	ds_read_b32 v79, v26 offset:460
	ds_read_b32 v80, v26 offset:592
	ds_read_b32 v81, v26 offset:724
	ds_read_b32 v82, v26 offset:856
	ds_read_b32 v83, v26 offset:988
	s_waitcnt lgkmcnt(0)
	v_pk_mul_f32 v[76:77], v[132:133], v[76:77]
	v_pk_mul_f32 v[78:79], v[134:135], v[78:79]
	v_pk_mul_f32 v[80:81], v[136:137], v[80:81]
	v_pk_mul_f32 v[82:83], v[138:139], v[82:83]
	v_cvt_pk_bf16_f32 v68, v76, v77
	v_cvt_pk_bf16_f32 v69, v78, v79
	v_cvt_pk_bf16_f32 v70, v80, v81
	v_cvt_pk_bf16_f32 v71, v82, v83
	global_store_dwordx4 v183, v[68:71], s[66:67]
	ds_read_b32 v76, v26 offset:96
	ds_read_b32 v77, v26 offset:228
	ds_read_b32 v78, v26 offset:360
	ds_read_b32 v79, v26 offset:492
	ds_read_b32 v80, v26 offset:624
	ds_read_b32 v81, v26 offset:756
	ds_read_b32 v82, v26 offset:888
	ds_read_b32 v83, v26 offset:1020
	s_waitcnt lgkmcnt(0)
	v_pk_mul_f32 v[76:77], v[132:133], v[76:77]
	v_pk_mul_f32 v[78:79], v[134:135], v[78:79]
	v_pk_mul_f32 v[80:81], v[136:137], v[80:81]
	v_pk_mul_f32 v[82:83], v[138:139], v[82:83]
	v_cvt_pk_bf16_f32 v72, v76, v77
	v_cvt_pk_bf16_f32 v73, v78, v79
	v_cvt_pk_bf16_f32 v74, v80, v81
	v_cvt_pk_bf16_f32 v75, v82, v83
	global_store_dwordx4 v184, v[72:75], s[66:67]
	s_add_i32 s70, s70, 1
	s_and_b32 s71, s70, 3
	s_cmp_eq_u32 s71, 0
	s_mov_b32 s79, 0x400
	s_cselect_b32 s71, 0x1fff400, s79
	s_add_u32 s66, s66, s71
	s_addc_u32 s67, s67, 0
	s_branch .Lmy_cvw1_done
.Lmy_cvw1_olast:
	s_waitcnt vmcnt(0)
	ds_write2_b32 v24, v140, v141 offset1:66
	ds_write2_b32 v24, v142, v143 offset0:132 offset1:198
	ds_write2_b32 v30, v144, v145 offset0:8 offset1:74
	ds_write2_b32 v30, v146, v147 offset0:140 offset1:206
	ds_write2_b32 v31, v148, v149 offset0:16 offset1:82
	ds_write2_b32 v31, v150, v151 offset0:148 offset1:214
	ds_write2_b32 v32, v152, v153 offset0:24 offset1:90
	ds_write2_b32 v32, v154, v155 offset0:156 offset1:222
	ds_write2_b32 v33, v156, v157 offset0:32 offset1:98
	ds_write2_b32 v33, v158, v159 offset0:164 offset1:230
	ds_write2_b32 v34, v160, v161 offset0:40 offset1:106
	ds_write2_b32 v34, v162, v163 offset0:172 offset1:238
	ds_write2_b32 v35, v164, v165 offset0:48 offset1:114
	ds_write2_b32 v35, v166, v167 offset0:180 offset1:246
	ds_write2_b32 v36, v168, v169 offset0:56 offset1:122
	ds_write2_b32 v36, v170, v171 offset0:188 offset1:254
	s_waitcnt lgkmcnt(0)
	ds_read_b32 v76, v26
	ds_read_b32 v77, v26 offset:132
	ds_read_b32 v78, v26 offset:264
	ds_read_b32 v79, v26 offset:396
	ds_read_b32 v80, v26 offset:528
	ds_read_b32 v81, v26 offset:660
	ds_read_b32 v82, v26 offset:792
	ds_read_b32 v83, v26 offset:924
	s_waitcnt lgkmcnt(0)
	v_pk_mul_f32 v[76:77], v[172:173], v[76:77]
	v_pk_mul_f32 v[78:79], v[174:175], v[78:79]
	v_pk_mul_f32 v[80:81], v[176:177], v[80:81]
	v_pk_mul_f32 v[82:83], v[178:179], v[82:83]
	v_cvt_pk_bf16_f32 v60, v76, v77
	v_cvt_pk_bf16_f32 v61, v78, v79
	v_cvt_pk_bf16_f32 v62, v80, v81
	v_cvt_pk_bf16_f32 v63, v82, v83
	global_store_dwordx4 v181, v[60:63], s[66:67]
	ds_read_b32 v76, v26 offset:32
	ds_read_b32 v77, v26 offset:164
	ds_read_b32 v78, v26 offset:296
	ds_read_b32 v79, v26 offset:428
	ds_read_b32 v80, v26 offset:560
	ds_read_b32 v81, v26 offset:692
	ds_read_b32 v82, v26 offset:824
	ds_read_b32 v83, v26 offset:956
	s_waitcnt lgkmcnt(0)
	v_pk_mul_f32 v[76:77], v[172:173], v[76:77]
	v_pk_mul_f32 v[78:79], v[174:175], v[78:79]
	v_pk_mul_f32 v[80:81], v[176:177], v[80:81]
	v_pk_mul_f32 v[82:83], v[178:179], v[82:83]
	v_cvt_pk_bf16_f32 v64, v76, v77
	v_cvt_pk_bf16_f32 v65, v78, v79
	v_cvt_pk_bf16_f32 v66, v80, v81
	v_cvt_pk_bf16_f32 v67, v82, v83
	global_store_dwordx4 v182, v[64:67], s[66:67]
	ds_read_b32 v76, v26 offset:64
	ds_read_b32 v77, v26 offset:196
	ds_read_b32 v78, v26 offset:328
	ds_read_b32 v79, v26 offset:460
	ds_read_b32 v80, v26 offset:592
	ds_read_b32 v81, v26 offset:724
	ds_read_b32 v82, v26 offset:856
	ds_read_b32 v83, v26 offset:988
	s_waitcnt lgkmcnt(0)
	v_pk_mul_f32 v[76:77], v[172:173], v[76:77]
	v_pk_mul_f32 v[78:79], v[174:175], v[78:79]
	v_pk_mul_f32 v[80:81], v[176:177], v[80:81]
	v_pk_mul_f32 v[82:83], v[178:179], v[82:83]
	v_cvt_pk_bf16_f32 v68, v76, v77
	v_cvt_pk_bf16_f32 v69, v78, v79
	v_cvt_pk_bf16_f32 v70, v80, v81
	v_cvt_pk_bf16_f32 v71, v82, v83
	global_store_dwordx4 v183, v[68:71], s[66:67]
	ds_read_b32 v76, v26 offset:96
	ds_read_b32 v77, v26 offset:228
	ds_read_b32 v78, v26 offset:360
	ds_read_b32 v79, v26 offset:492
	ds_read_b32 v80, v26 offset:624
	ds_read_b32 v81, v26 offset:756
	ds_read_b32 v82, v26 offset:888
	ds_read_b32 v83, v26 offset:1020
	s_waitcnt lgkmcnt(0)
	v_pk_mul_f32 v[76:77], v[172:173], v[76:77]
	v_pk_mul_f32 v[78:79], v[174:175], v[78:79]
	v_pk_mul_f32 v[80:81], v[176:177], v[80:81]
	v_pk_mul_f32 v[82:83], v[178:179], v[82:83]
	v_cvt_pk_bf16_f32 v72, v76, v77
	v_cvt_pk_bf16_f32 v73, v78, v79
	v_cvt_pk_bf16_f32 v74, v80, v81
	v_cvt_pk_bf16_f32 v75, v82, v83
	global_store_dwordx4 v184, v[72:75], s[66:67]
	s_add_i32 s70, s70, 1
	s_and_b32 s71, s70, 3
	s_cmp_eq_u32 s71, 0
	s_mov_b32 s79, 0x400
	s_cselect_b32 s71, 0x1fff400, s79
	s_add_u32 s66, s66, s71
	s_addc_u32 s67, s67, 0
.Lmy_cvw1_done:
	v_lshlrev_b32_e32 v180, 13, v1
	v_or_b32_e32 v180, v180, v16
	v_or_b32_e32 v181, 0, v25
	v_lshlrev_b32_e32 v181, 14, v181
	v_or_b32_e32 v181, v181, v18
	v_or_b32_e32 v182, 8, v25
	v_lshlrev_b32_e32 v182, 14, v182
	v_or_b32_e32 v182, v182, v18
	v_or_b32_e32 v183, 16, v25
	v_lshlrev_b32_e32 v183, 14, v183
	v_or_b32_e32 v183, v183, v18
	v_or_b32_e32 v184, 24, v25
	v_lshlrev_b32_e32 v184, 14, v184
	v_or_b32_e32 v184, v184, v18
	v_readlane_b32 s64, v253, 33
	v_readlane_b32 s65, v253, 34
	s_lshr_b32 s77, s76, 6
	s_and_b32 s78, s76, 63
	s_lshl_b32 s79, s77, 19
	s_add_u32 s64, s64, s79
	s_addc_u32 s65, s65, 0
	s_lshl_b32 s79, s78, 7
	s_add_u32 s64, s64, s79
	s_addc_u32 s65, s65, 0
	s_lshl_b32 s79, s78, 19
	s_add_u32 s66, s24, s79
	s_addc_u32 s67, s25, 0
	s_lshl_b32 s79, s77, 7
	s_add_u32 s66, s66, s79
	s_addc_u32 s67, s67, 0
	s_mov_b32 s78, 12
	s_mov_b32 s70, 0
	s_mov_b64 s[72:73], s[64:65]
	global_load_dword v100, v180, s[72:73]
	s_add_u32 s72, s72, 0x4000
	s_addc_u32 s73, s73, 0
	global_load_dword v101, v180, s[72:73]
	s_add_u32 s72, s72, 0x4000
	s_addc_u32 s73, s73, 0
	global_load_dword v102, v180, s[72:73]
	s_add_u32 s72, s72, 0x4000
	s_addc_u32 s73, s73, 0
	global_load_dword v103, v180, s[72:73]
	s_add_u32 s72, s72, 0x4000
	s_addc_u32 s73, s73, 0
	global_load_dword v104, v180, s[72:73]
	s_add_u32 s72, s72, 0x4000
	s_addc_u32 s73, s73, 0
	global_load_dword v105, v180, s[72:73]
	s_add_u32 s72, s72, 0x4000
	s_addc_u32 s73, s73, 0
	global_load_dword v106, v180, s[72:73]
	s_add_u32 s72, s72, 0x4000
	s_addc_u32 s73, s73, 0
	global_load_dword v107, v180, s[72:73]
	s_add_u32 s72, s72, 0x4000
	s_addc_u32 s73, s73, 0
	global_load_dword v108, v180, s[72:73]
	s_add_u32 s72, s72, 0x4000
	s_addc_u32 s73, s73, 0
	global_load_dword v109, v180, s[72:73]
	s_add_u32 s72, s72, 0x4000
	s_addc_u32 s73, s73, 0
	global_load_dword v110, v180, s[72:73]
	s_add_u32 s72, s72, 0x4000
	s_addc_u32 s73, s73, 0
	global_load_dword v111, v180, s[72:73]
	s_add_u32 s72, s72, 0x4000
	s_addc_u32 s73, s73, 0
	global_load_dword v112, v180, s[72:73]
	s_add_u32 s72, s72, 0x4000
	s_addc_u32 s73, s73, 0
	global_load_dword v113, v180, s[72:73]
	s_add_u32 s72, s72, 0x4000
	s_addc_u32 s73, s73, 0
	global_load_dword v114, v180, s[72:73]
	s_add_u32 s72, s72, 0x4000
	s_addc_u32 s73, s73, 0
	global_load_dword v115, v180, s[72:73]
	s_add_u32 s72, s72, 0x4000
	s_addc_u32 s73, s73, 0
	global_load_dword v116, v180, s[72:73]
	s_add_u32 s72, s72, 0x4000
	s_addc_u32 s73, s73, 0
	global_load_dword v117, v180, s[72:73]
	s_add_u32 s72, s72, 0x4000
	s_addc_u32 s73, s73, 0
	global_load_dword v118, v180, s[72:73]
	s_add_u32 s72, s72, 0x4000
	s_addc_u32 s73, s73, 0
	global_load_dword v119, v180, s[72:73]
	s_add_u32 s72, s72, 0x4000
	s_addc_u32 s73, s73, 0
	global_load_dword v120, v180, s[72:73]
	s_add_u32 s72, s72, 0x4000
	s_addc_u32 s73, s73, 0
	global_load_dword v121, v180, s[72:73]
	s_add_u32 s72, s72, 0x4000
	s_addc_u32 s73, s73, 0
	global_load_dword v122, v180, s[72:73]
	s_add_u32 s72, s72, 0x4000
	s_addc_u32 s73, s73, 0
	global_load_dword v123, v180, s[72:73]
	s_add_u32 s72, s72, 0x4000
	s_addc_u32 s73, s73, 0
	global_load_dword v124, v180, s[72:73]
	s_add_u32 s72, s72, 0x4000
	s_addc_u32 s73, s73, 0
	global_load_dword v125, v180, s[72:73]
	s_add_u32 s72, s72, 0x4000
	s_addc_u32 s73, s73, 0
	global_load_dword v126, v180, s[72:73]
	s_add_u32 s72, s72, 0x4000
	s_addc_u32 s73, s73, 0
	global_load_dword v127, v180, s[72:73]
	s_add_u32 s72, s72, 0x4000
	s_addc_u32 s73, s73, 0
	global_load_dword v128, v180, s[72:73]
	s_add_u32 s72, s72, 0x4000
	s_addc_u32 s73, s73, 0
	global_load_dword v129, v180, s[72:73]
	s_add_u32 s72, s72, 0x4000
	s_addc_u32 s73, s73, 0
	global_load_dword v130, v180, s[72:73]
	s_add_u32 s72, s72, 0x4000
	s_addc_u32 s73, s73, 0
	global_load_dword v131, v180, s[72:73]
	s_add_u32 s64, s64, 0x1000000
	s_addc_u32 s65, s65, 0
.Lmy_cvw2_loop:
	s_add_i32 s71, s70, 1
	s_cmp_lt_u32 s71, s78
	s_cbranch_scc0 .Lmy_cvw2_elast
	s_mov_b64 s[72:73], s[64:65]
	global_load_dword v140, v180, s[72:73]
	s_add_u32 s72, s72, 0x4000
	s_addc_u32 s73, s73, 0
	global_load_dword v141, v180, s[72:73]
	s_add_u32 s72, s72, 0x4000
	s_addc_u32 s73, s73, 0
	global_load_dword v142, v180, s[72:73]
	s_add_u32 s72, s72, 0x4000
	s_addc_u32 s73, s73, 0
	global_load_dword v143, v180, s[72:73]
	s_add_u32 s72, s72, 0x4000
	s_addc_u32 s73, s73, 0
	global_load_dword v144, v180, s[72:73]
	s_add_u32 s72, s72, 0x4000
	s_addc_u32 s73, s73, 0
	global_load_dword v145, v180, s[72:73]
	s_add_u32 s72, s72, 0x4000
	s_addc_u32 s73, s73, 0
	global_load_dword v146, v180, s[72:73]
	s_add_u32 s72, s72, 0x4000
	s_addc_u32 s73, s73, 0
	global_load_dword v147, v180, s[72:73]
	s_add_u32 s72, s72, 0x4000
	s_addc_u32 s73, s73, 0
	global_load_dword v148, v180, s[72:73]
	s_add_u32 s72, s72, 0x4000
	s_addc_u32 s73, s73, 0
	global_load_dword v149, v180, s[72:73]
	s_add_u32 s72, s72, 0x4000
	s_addc_u32 s73, s73, 0
	global_load_dword v150, v180, s[72:73]
	s_add_u32 s72, s72, 0x4000
	s_addc_u32 s73, s73, 0
	global_load_dword v151, v180, s[72:73]
	s_add_u32 s72, s72, 0x4000
	s_addc_u32 s73, s73, 0
	global_load_dword v152, v180, s[72:73]
	s_add_u32 s72, s72, 0x4000
	s_addc_u32 s73, s73, 0
	global_load_dword v153, v180, s[72:73]
	s_add_u32 s72, s72, 0x4000
	s_addc_u32 s73, s73, 0
	global_load_dword v154, v180, s[72:73]
	s_add_u32 s72, s72, 0x4000
	s_addc_u32 s73, s73, 0
	global_load_dword v155, v180, s[72:73]
	s_add_u32 s72, s72, 0x4000
	s_addc_u32 s73, s73, 0
	global_load_dword v156, v180, s[72:73]
	s_add_u32 s72, s72, 0x4000
	s_addc_u32 s73, s73, 0
	global_load_dword v157, v180, s[72:73]
	s_add_u32 s72, s72, 0x4000
	s_addc_u32 s73, s73, 0
	global_load_dword v158, v180, s[72:73]
	s_add_u32 s72, s72, 0x4000
	s_addc_u32 s73, s73, 0
	global_load_dword v159, v180, s[72:73]
	s_add_u32 s72, s72, 0x4000
	s_addc_u32 s73, s73, 0
	global_load_dword v160, v180, s[72:73]
	s_add_u32 s72, s72, 0x4000
	s_addc_u32 s73, s73, 0
	global_load_dword v161, v180, s[72:73]
	s_add_u32 s72, s72, 0x4000
	s_addc_u32 s73, s73, 0
	global_load_dword v162, v180, s[72:73]
	s_add_u32 s72, s72, 0x4000
	s_addc_u32 s73, s73, 0
	global_load_dword v163, v180, s[72:73]
	s_add_u32 s72, s72, 0x4000
	s_addc_u32 s73, s73, 0
	global_load_dword v164, v180, s[72:73]
	s_add_u32 s72, s72, 0x4000
	s_addc_u32 s73, s73, 0
	global_load_dword v165, v180, s[72:73]
	s_add_u32 s72, s72, 0x4000
	s_addc_u32 s73, s73, 0
	global_load_dword v166, v180, s[72:73]
	s_add_u32 s72, s72, 0x4000
	s_addc_u32 s73, s73, 0
	global_load_dword v167, v180, s[72:73]
	s_add_u32 s72, s72, 0x4000
	s_addc_u32 s73, s73, 0
	global_load_dword v168, v180, s[72:73]
	s_add_u32 s72, s72, 0x4000
	s_addc_u32 s73, s73, 0
	global_load_dword v169, v180, s[72:73]
	s_add_u32 s72, s72, 0x4000
	s_addc_u32 s73, s73, 0
	global_load_dword v170, v180, s[72:73]
	s_add_u32 s72, s72, 0x4000
	s_addc_u32 s73, s73, 0
	global_load_dword v171, v180, s[72:73]
	s_add_u32 s64, s64, 0x1000000
	s_addc_u32 s65, s65, 0
	s_waitcnt vmcnt(32)
	ds_write2_b32 v24, v100, v101 offset1:66
	ds_write2_b32 v24, v102, v103 offset0:132 offset1:198
	ds_write2_b32 v30, v104, v105 offset0:8 offset1:74
	ds_write2_b32 v30, v106, v107 offset0:140 offset1:206
	ds_write2_b32 v31, v108, v109 offset0:16 offset1:82
	ds_write2_b32 v31, v110, v111 offset0:148 offset1:214
	ds_write2_b32 v32, v112, v113 offset0:24 offset1:90
	ds_write2_b32 v32, v114, v115 offset0:156 offset1:222
	ds_write2_b32 v33, v116, v117 offset0:32 offset1:98
	ds_write2_b32 v33, v118, v119 offset0:164 offset1:230
	ds_write2_b32 v34, v120, v121 offset0:40 offset1:106
	ds_write2_b32 v34, v122, v123 offset0:172 offset1:238
	ds_write2_b32 v35, v124, v125 offset0:48 offset1:114
	ds_write2_b32 v35, v126, v127 offset0:180 offset1:246
	ds_write2_b32 v36, v128, v129 offset0:56 offset1:122
	ds_write2_b32 v36, v130, v131 offset0:188 offset1:254
	s_waitcnt lgkmcnt(0)
	ds_read_b32 v76, v26
	ds_read_b32 v77, v26 offset:132
	ds_read_b32 v78, v26 offset:264
	ds_read_b32 v79, v26 offset:396
	ds_read_b32 v80, v26 offset:528
	ds_read_b32 v81, v26 offset:660
	ds_read_b32 v82, v26 offset:792
	ds_read_b32 v83, v26 offset:924
	s_waitcnt lgkmcnt(0)
	v_cvt_pk_bf16_f32 v60, v76, v77
	v_cvt_pk_bf16_f32 v61, v78, v79
	v_cvt_pk_bf16_f32 v62, v80, v81
	v_cvt_pk_bf16_f32 v63, v82, v83
	global_store_dwordx4 v181, v[60:63], s[66:67]
	ds_read_b32 v76, v26 offset:32
	ds_read_b32 v77, v26 offset:164
	ds_read_b32 v78, v26 offset:296
	ds_read_b32 v79, v26 offset:428
	ds_read_b32 v80, v26 offset:560
	ds_read_b32 v81, v26 offset:692
	ds_read_b32 v82, v26 offset:824
	ds_read_b32 v83, v26 offset:956
	s_waitcnt lgkmcnt(0)
	v_cvt_pk_bf16_f32 v64, v76, v77
	v_cvt_pk_bf16_f32 v65, v78, v79
	v_cvt_pk_bf16_f32 v66, v80, v81
	v_cvt_pk_bf16_f32 v67, v82, v83
	global_store_dwordx4 v182, v[64:67], s[66:67]
	ds_read_b32 v76, v26 offset:64
	ds_read_b32 v77, v26 offset:196
	ds_read_b32 v78, v26 offset:328
	ds_read_b32 v79, v26 offset:460
	ds_read_b32 v80, v26 offset:592
	ds_read_b32 v81, v26 offset:724
	ds_read_b32 v82, v26 offset:856
	ds_read_b32 v83, v26 offset:988
	s_waitcnt lgkmcnt(0)
	v_cvt_pk_bf16_f32 v68, v76, v77
	v_cvt_pk_bf16_f32 v69, v78, v79
	v_cvt_pk_bf16_f32 v70, v80, v81
	v_cvt_pk_bf16_f32 v71, v82, v83
	global_store_dwordx4 v183, v[68:71], s[66:67]
	ds_read_b32 v76, v26 offset:96
	ds_read_b32 v77, v26 offset:228
	ds_read_b32 v78, v26 offset:360
	ds_read_b32 v79, v26 offset:492
	ds_read_b32 v80, v26 offset:624
	ds_read_b32 v81, v26 offset:756
	ds_read_b32 v82, v26 offset:888
	ds_read_b32 v83, v26 offset:1020
	s_waitcnt lgkmcnt(0)
	v_cvt_pk_bf16_f32 v72, v76, v77
	v_cvt_pk_bf16_f32 v73, v78, v79
	v_cvt_pk_bf16_f32 v74, v80, v81
	v_cvt_pk_bf16_f32 v75, v82, v83
	global_store_dwordx4 v184, v[72:75], s[66:67]
	s_add_i32 s70, s70, 1
	s_and_b32 s71, s70, 3
	s_cmp_eq_u32 s71, 0
	s_mov_b32 s79, 0x1000
	s_cselect_b32 s71, 0x1ffd000, s79
	s_add_u32 s66, s66, s71
	s_addc_u32 s67, s67, 0
	s_add_i32 s71, s70, 1
	s_cmp_lt_u32 s71, s78
	s_cbranch_scc0 .Lmy_cvw2_olast
	s_mov_b64 s[72:73], s[64:65]
	global_load_dword v100, v180, s[72:73]
	s_add_u32 s72, s72, 0x4000
	s_addc_u32 s73, s73, 0
	global_load_dword v101, v180, s[72:73]
	s_add_u32 s72, s72, 0x4000
	s_addc_u32 s73, s73, 0
	global_load_dword v102, v180, s[72:73]
	s_add_u32 s72, s72, 0x4000
	s_addc_u32 s73, s73, 0
	global_load_dword v103, v180, s[72:73]
	s_add_u32 s72, s72, 0x4000
	s_addc_u32 s73, s73, 0
	global_load_dword v104, v180, s[72:73]
	s_add_u32 s72, s72, 0x4000
	s_addc_u32 s73, s73, 0
	global_load_dword v105, v180, s[72:73]
	s_add_u32 s72, s72, 0x4000
	s_addc_u32 s73, s73, 0
	global_load_dword v106, v180, s[72:73]
	s_add_u32 s72, s72, 0x4000
	s_addc_u32 s73, s73, 0
	global_load_dword v107, v180, s[72:73]
	s_add_u32 s72, s72, 0x4000
	s_addc_u32 s73, s73, 0
	global_load_dword v108, v180, s[72:73]
	s_add_u32 s72, s72, 0x4000
	s_addc_u32 s73, s73, 0
	global_load_dword v109, v180, s[72:73]
	s_add_u32 s72, s72, 0x4000
	s_addc_u32 s73, s73, 0
	global_load_dword v110, v180, s[72:73]
	s_add_u32 s72, s72, 0x4000
	s_addc_u32 s73, s73, 0
	global_load_dword v111, v180, s[72:73]
	s_add_u32 s72, s72, 0x4000
	s_addc_u32 s73, s73, 0
	global_load_dword v112, v180, s[72:73]
	s_add_u32 s72, s72, 0x4000
	s_addc_u32 s73, s73, 0
	global_load_dword v113, v180, s[72:73]
	s_add_u32 s72, s72, 0x4000
	s_addc_u32 s73, s73, 0
	global_load_dword v114, v180, s[72:73]
	s_add_u32 s72, s72, 0x4000
	s_addc_u32 s73, s73, 0
	global_load_dword v115, v180, s[72:73]
	s_add_u32 s72, s72, 0x4000
	s_addc_u32 s73, s73, 0
	global_load_dword v116, v180, s[72:73]
	s_add_u32 s72, s72, 0x4000
	s_addc_u32 s73, s73, 0
	global_load_dword v117, v180, s[72:73]
	s_add_u32 s72, s72, 0x4000
	s_addc_u32 s73, s73, 0
	global_load_dword v118, v180, s[72:73]
	s_add_u32 s72, s72, 0x4000
	s_addc_u32 s73, s73, 0
	global_load_dword v119, v180, s[72:73]
	s_add_u32 s72, s72, 0x4000
	s_addc_u32 s73, s73, 0
	global_load_dword v120, v180, s[72:73]
	s_add_u32 s72, s72, 0x4000
	s_addc_u32 s73, s73, 0
	global_load_dword v121, v180, s[72:73]
	s_add_u32 s72, s72, 0x4000
	s_addc_u32 s73, s73, 0
	global_load_dword v122, v180, s[72:73]
	s_add_u32 s72, s72, 0x4000
	s_addc_u32 s73, s73, 0
	global_load_dword v123, v180, s[72:73]
	s_add_u32 s72, s72, 0x4000
	s_addc_u32 s73, s73, 0
	global_load_dword v124, v180, s[72:73]
	s_add_u32 s72, s72, 0x4000
	s_addc_u32 s73, s73, 0
	global_load_dword v125, v180, s[72:73]
	s_add_u32 s72, s72, 0x4000
	s_addc_u32 s73, s73, 0
	global_load_dword v126, v180, s[72:73]
	s_add_u32 s72, s72, 0x4000
	s_addc_u32 s73, s73, 0
	global_load_dword v127, v180, s[72:73]
	s_add_u32 s72, s72, 0x4000
	s_addc_u32 s73, s73, 0
	global_load_dword v128, v180, s[72:73]
	s_add_u32 s72, s72, 0x4000
	s_addc_u32 s73, s73, 0
	global_load_dword v129, v180, s[72:73]
	s_add_u32 s72, s72, 0x4000
	s_addc_u32 s73, s73, 0
	global_load_dword v130, v180, s[72:73]
	s_add_u32 s72, s72, 0x4000
	s_addc_u32 s73, s73, 0
	global_load_dword v131, v180, s[72:73]
	s_add_u32 s64, s64, 0x1000000
	s_addc_u32 s65, s65, 0
	s_waitcnt vmcnt(32)
	ds_write2_b32 v24, v140, v141 offset1:66
	ds_write2_b32 v24, v142, v143 offset0:132 offset1:198
	ds_write2_b32 v30, v144, v145 offset0:8 offset1:74
	ds_write2_b32 v30, v146, v147 offset0:140 offset1:206
	ds_write2_b32 v31, v148, v149 offset0:16 offset1:82
	ds_write2_b32 v31, v150, v151 offset0:148 offset1:214
	ds_write2_b32 v32, v152, v153 offset0:24 offset1:90
	ds_write2_b32 v32, v154, v155 offset0:156 offset1:222
	ds_write2_b32 v33, v156, v157 offset0:32 offset1:98
	ds_write2_b32 v33, v158, v159 offset0:164 offset1:230
	ds_write2_b32 v34, v160, v161 offset0:40 offset1:106
	ds_write2_b32 v34, v162, v163 offset0:172 offset1:238
	ds_write2_b32 v35, v164, v165 offset0:48 offset1:114
	ds_write2_b32 v35, v166, v167 offset0:180 offset1:246
	ds_write2_b32 v36, v168, v169 offset0:56 offset1:122
	ds_write2_b32 v36, v170, v171 offset0:188 offset1:254
	s_waitcnt lgkmcnt(0)
	ds_read_b32 v76, v26
	ds_read_b32 v77, v26 offset:132
	ds_read_b32 v78, v26 offset:264
	ds_read_b32 v79, v26 offset:396
	ds_read_b32 v80, v26 offset:528
	ds_read_b32 v81, v26 offset:660
	ds_read_b32 v82, v26 offset:792
	ds_read_b32 v83, v26 offset:924
	s_waitcnt lgkmcnt(0)
	v_cvt_pk_bf16_f32 v60, v76, v77
	v_cvt_pk_bf16_f32 v61, v78, v79
	v_cvt_pk_bf16_f32 v62, v80, v81
	v_cvt_pk_bf16_f32 v63, v82, v83
	global_store_dwordx4 v181, v[60:63], s[66:67]
	ds_read_b32 v76, v26 offset:32
	ds_read_b32 v77, v26 offset:164
	ds_read_b32 v78, v26 offset:296
	ds_read_b32 v79, v26 offset:428
	ds_read_b32 v80, v26 offset:560
	ds_read_b32 v81, v26 offset:692
	ds_read_b32 v82, v26 offset:824
	ds_read_b32 v83, v26 offset:956
	s_waitcnt lgkmcnt(0)
	v_cvt_pk_bf16_f32 v64, v76, v77
	v_cvt_pk_bf16_f32 v65, v78, v79
	v_cvt_pk_bf16_f32 v66, v80, v81
	v_cvt_pk_bf16_f32 v67, v82, v83
	global_store_dwordx4 v182, v[64:67], s[66:67]
	ds_read_b32 v76, v26 offset:64
	ds_read_b32 v77, v26 offset:196
	ds_read_b32 v78, v26 offset:328
	ds_read_b32 v79, v26 offset:460
	ds_read_b32 v80, v26 offset:592
	ds_read_b32 v81, v26 offset:724
	ds_read_b32 v82, v26 offset:856
	ds_read_b32 v83, v26 offset:988
	s_waitcnt lgkmcnt(0)
	v_cvt_pk_bf16_f32 v68, v76, v77
	v_cvt_pk_bf16_f32 v69, v78, v79
	v_cvt_pk_bf16_f32 v70, v80, v81
	v_cvt_pk_bf16_f32 v71, v82, v83
	global_store_dwordx4 v183, v[68:71], s[66:67]
	ds_read_b32 v76, v26 offset:96
	ds_read_b32 v77, v26 offset:228
	ds_read_b32 v78, v26 offset:360
	ds_read_b32 v79, v26 offset:492
	ds_read_b32 v80, v26 offset:624
	ds_read_b32 v81, v26 offset:756
	ds_read_b32 v82, v26 offset:888
	ds_read_b32 v83, v26 offset:1020
	s_waitcnt lgkmcnt(0)
	v_cvt_pk_bf16_f32 v72, v76, v77
	v_cvt_pk_bf16_f32 v73, v78, v79
	v_cvt_pk_bf16_f32 v74, v80, v81
	v_cvt_pk_bf16_f32 v75, v82, v83
	global_store_dwordx4 v184, v[72:75], s[66:67]
	s_add_i32 s70, s70, 1
	s_and_b32 s71, s70, 3
	s_cmp_eq_u32 s71, 0
	s_mov_b32 s79, 0x1000
	s_cselect_b32 s71, 0x1ffd000, s79
	s_add_u32 s66, s66, s71
	s_addc_u32 s67, s67, 0
	s_branch .Lmy_cvw2_loop
.Lmy_cvw2_elast:
	s_waitcnt vmcnt(0)
	ds_write2_b32 v24, v100, v101 offset1:66
	ds_write2_b32 v24, v102, v103 offset0:132 offset1:198
	ds_write2_b32 v30, v104, v105 offset0:8 offset1:74
	ds_write2_b32 v30, v106, v107 offset0:140 offset1:206
	ds_write2_b32 v31, v108, v109 offset0:16 offset1:82
	ds_write2_b32 v31, v110, v111 offset0:148 offset1:214
	ds_write2_b32 v32, v112, v113 offset0:24 offset1:90
	ds_write2_b32 v32, v114, v115 offset0:156 offset1:222
	ds_write2_b32 v33, v116, v117 offset0:32 offset1:98
	ds_write2_b32 v33, v118, v119 offset0:164 offset1:230
	ds_write2_b32 v34, v120, v121 offset0:40 offset1:106
	ds_write2_b32 v34, v122, v123 offset0:172 offset1:238
	ds_write2_b32 v35, v124, v125 offset0:48 offset1:114
	ds_write2_b32 v35, v126, v127 offset0:180 offset1:246
	ds_write2_b32 v36, v128, v129 offset0:56 offset1:122
	ds_write2_b32 v36, v130, v131 offset0:188 offset1:254
	s_waitcnt lgkmcnt(0)
	ds_read_b32 v76, v26
	ds_read_b32 v77, v26 offset:132
	ds_read_b32 v78, v26 offset:264
	ds_read_b32 v79, v26 offset:396
	ds_read_b32 v80, v26 offset:528
	ds_read_b32 v81, v26 offset:660
	ds_read_b32 v82, v26 offset:792
	ds_read_b32 v83, v26 offset:924
	s_waitcnt lgkmcnt(0)
	v_cvt_pk_bf16_f32 v60, v76, v77
	v_cvt_pk_bf16_f32 v61, v78, v79
	v_cvt_pk_bf16_f32 v62, v80, v81
	v_cvt_pk_bf16_f32 v63, v82, v83
	global_store_dwordx4 v181, v[60:63], s[66:67]
	ds_read_b32 v76, v26 offset:32
	ds_read_b32 v77, v26 offset:164
	ds_read_b32 v78, v26 offset:296
	ds_read_b32 v79, v26 offset:428
	ds_read_b32 v80, v26 offset:560
	ds_read_b32 v81, v26 offset:692
	ds_read_b32 v82, v26 offset:824
	ds_read_b32 v83, v26 offset:956
	s_waitcnt lgkmcnt(0)
	v_cvt_pk_bf16_f32 v64, v76, v77
	v_cvt_pk_bf16_f32 v65, v78, v79
	v_cvt_pk_bf16_f32 v66, v80, v81
	v_cvt_pk_bf16_f32 v67, v82, v83
	global_store_dwordx4 v182, v[64:67], s[66:67]
	ds_read_b32 v76, v26 offset:64
	ds_read_b32 v77, v26 offset:196
	ds_read_b32 v78, v26 offset:328
	ds_read_b32 v79, v26 offset:460
	ds_read_b32 v80, v26 offset:592
	ds_read_b32 v81, v26 offset:724
	ds_read_b32 v82, v26 offset:856
	ds_read_b32 v83, v26 offset:988
	s_waitcnt lgkmcnt(0)
	v_cvt_pk_bf16_f32 v68, v76, v77
	v_cvt_pk_bf16_f32 v69, v78, v79
	v_cvt_pk_bf16_f32 v70, v80, v81
	v_cvt_pk_bf16_f32 v71, v82, v83
	global_store_dwordx4 v183, v[68:71], s[66:67]
	ds_read_b32 v76, v26 offset:96
	ds_read_b32 v77, v26 offset:228
	ds_read_b32 v78, v26 offset:360
	ds_read_b32 v79, v26 offset:492
	ds_read_b32 v80, v26 offset:624
	ds_read_b32 v81, v26 offset:756
	ds_read_b32 v82, v26 offset:888
	ds_read_b32 v83, v26 offset:1020
	s_waitcnt lgkmcnt(0)
	v_cvt_pk_bf16_f32 v72, v76, v77
	v_cvt_pk_bf16_f32 v73, v78, v79
	v_cvt_pk_bf16_f32 v74, v80, v81
	v_cvt_pk_bf16_f32 v75, v82, v83
	global_store_dwordx4 v184, v[72:75], s[66:67]
	s_add_i32 s70, s70, 1
	s_and_b32 s71, s70, 3
	s_cmp_eq_u32 s71, 0
	s_mov_b32 s79, 0x1000
	s_cselect_b32 s71, 0x1ffd000, s79
	s_add_u32 s66, s66, s71
	s_addc_u32 s67, s67, 0
	s_branch .Lmy_cvw2_done
.Lmy_cvw2_olast:
	s_waitcnt vmcnt(0)
	ds_write2_b32 v24, v140, v141 offset1:66
	ds_write2_b32 v24, v142, v143 offset0:132 offset1:198
	ds_write2_b32 v30, v144, v145 offset0:8 offset1:74
	ds_write2_b32 v30, v146, v147 offset0:140 offset1:206
	ds_write2_b32 v31, v148, v149 offset0:16 offset1:82
	ds_write2_b32 v31, v150, v151 offset0:148 offset1:214
	ds_write2_b32 v32, v152, v153 offset0:24 offset1:90
	ds_write2_b32 v32, v154, v155 offset0:156 offset1:222
	ds_write2_b32 v33, v156, v157 offset0:32 offset1:98
	ds_write2_b32 v33, v158, v159 offset0:164 offset1:230
	ds_write2_b32 v34, v160, v161 offset0:40 offset1:106
	ds_write2_b32 v34, v162, v163 offset0:172 offset1:238
	ds_write2_b32 v35, v164, v165 offset0:48 offset1:114
	ds_write2_b32 v35, v166, v167 offset0:180 offset1:246
	ds_write2_b32 v36, v168, v169 offset0:56 offset1:122
	ds_write2_b32 v36, v170, v171 offset0:188 offset1:254
	s_waitcnt lgkmcnt(0)
	ds_read_b32 v76, v26
	ds_read_b32 v77, v26 offset:132
	ds_read_b32 v78, v26 offset:264
	ds_read_b32 v79, v26 offset:396
	ds_read_b32 v80, v26 offset:528
	ds_read_b32 v81, v26 offset:660
	ds_read_b32 v82, v26 offset:792
	ds_read_b32 v83, v26 offset:924
	s_waitcnt lgkmcnt(0)
	v_cvt_pk_bf16_f32 v60, v76, v77
	v_cvt_pk_bf16_f32 v61, v78, v79
	v_cvt_pk_bf16_f32 v62, v80, v81
	v_cvt_pk_bf16_f32 v63, v82, v83
	global_store_dwordx4 v181, v[60:63], s[66:67]
	ds_read_b32 v76, v26 offset:32
	ds_read_b32 v77, v26 offset:164
	ds_read_b32 v78, v26 offset:296
	ds_read_b32 v79, v26 offset:428
	ds_read_b32 v80, v26 offset:560
	ds_read_b32 v81, v26 offset:692
	ds_read_b32 v82, v26 offset:824
	ds_read_b32 v83, v26 offset:956
	s_waitcnt lgkmcnt(0)
	v_cvt_pk_bf16_f32 v64, v76, v77
	v_cvt_pk_bf16_f32 v65, v78, v79
	v_cvt_pk_bf16_f32 v66, v80, v81
	v_cvt_pk_bf16_f32 v67, v82, v83
	global_store_dwordx4 v182, v[64:67], s[66:67]
	ds_read_b32 v76, v26 offset:64
	ds_read_b32 v77, v26 offset:196
	ds_read_b32 v78, v26 offset:328
	ds_read_b32 v79, v26 offset:460
	ds_read_b32 v80, v26 offset:592
	ds_read_b32 v81, v26 offset:724
	ds_read_b32 v82, v26 offset:856
	ds_read_b32 v83, v26 offset:988
	s_waitcnt lgkmcnt(0)
	v_cvt_pk_bf16_f32 v68, v76, v77
	v_cvt_pk_bf16_f32 v69, v78, v79
	v_cvt_pk_bf16_f32 v70, v80, v81
	v_cvt_pk_bf16_f32 v71, v82, v83
	global_store_dwordx4 v183, v[68:71], s[66:67]
	ds_read_b32 v76, v26 offset:96
	ds_read_b32 v77, v26 offset:228
	ds_read_b32 v78, v26 offset:360
	ds_read_b32 v79, v26 offset:492
	ds_read_b32 v80, v26 offset:624
	ds_read_b32 v81, v26 offset:756
	ds_read_b32 v82, v26 offset:888
	ds_read_b32 v83, v26 offset:1020
	s_waitcnt lgkmcnt(0)
	v_cvt_pk_bf16_f32 v72, v76, v77
	v_cvt_pk_bf16_f32 v73, v78, v79
	v_cvt_pk_bf16_f32 v74, v80, v81
	v_cvt_pk_bf16_f32 v75, v82, v83
	global_store_dwordx4 v184, v[72:75], s[66:67]
	s_add_i32 s70, s70, 1
	s_and_b32 s71, s70, 3
	s_cmp_eq_u32 s71, 0
	s_mov_b32 s79, 0x1000
	s_cselect_b32 s71, 0x1ffd000, s79
	s_add_u32 s66, s66, s71
	s_addc_u32 s67, s67, 0
.Lmy_cvw2_done:
	s_lshl_b32 s79, s86, 5
	s_add_i32 s28, s28, s79
	s_lshl_b32 s79, s30, 5
	s_add_i32 s29, s29, s79
	s_waitcnt vmcnt(0) lgkmcnt(0)
	v_readlane_b32 s64, v253, 4
	v_readlane_b32 s65, v253, 5
	v_readlane_b32 s66, v253, 6
	v_readlane_b32 s67, v253, 7
	v_readlane_b32 s68, v253, 8
	v_readlane_b32 s69, v253, 9
	v_readlane_b32 s70, v253, 10
	v_readlane_b32 s71, v253, 11
	v_readlane_b32 s72, v253, 12
	v_readlane_b32 s73, v253, 13
.Lmy_cv_skip:
	s_branch .LBB0_12
.LBB0_9:
	s_waitcnt vmcnt(0)
	v_mov_b32_e32 v6, 1.0
	v_mov_b32_e32 v7, v6
	v_mov_b32_e32 v8, v6
	v_mov_b32_e32 v9, v6
	v_mov_b32_e32 v2, v6
	v_mov_b32_e32 v3, v6
	v_mov_b32_e32 v4, v6
	v_mov_b32_e32 v5, v6

.Lmy_deferred:
	s_cmp_lg_u32 s96, 0x100
	s_cbranch_scc1 .LBB0_183
	s_lshr_b32 s24, s8, 6
	s_sub_i32 s25, s26, 64
	s_lshl_b32 s25, s25, 3
	s_add_i32 s24, s25, s24
	v_and_b32_e32 v4, 31, v193
	v_bfe_u32 v1, v193, 5, 1
	v_and_b32_e32 v5, 7, v193
	v_bfe_u32 v25, v193, 3, 3
	s_lshr_b32 s27, s8, 6
	s_lshl_b32 s27, s27, 14
	v_lshl_or_b32 v3, v4, 2, s27
	s_movk_i32 s28, 0x84
	v_mad_u32_u24 v24, v1, s28, v3
	v_mul_u32_u24_e32 v2, 0x420, v5
	v_lshlrev_b32_e32 v3, 2, v25
	v_or3_b32 v26, s27, v2, v3
	v_add_u32_e32 v30, 0x400, v24
	v_add_u32_e32 v31, 0x800, v24
	v_add_u32_e32 v32, 0xc00, v24
	v_add_u32_e32 v33, 0x1000, v24
	v_add_u32_e32 v34, 0x1400, v24
	v_add_u32_e32 v35, 0x1800, v24
	v_add_u32_e32 v36, 0x1c00, v24
	v_lshlrev_b32_e32 v16, 2, v4
	v_lshlrev_b32_e32 v18, 4, v5
	v_lshlrev_b32_e32 v20, 5, v5
	s_cmp_lt_u32 s24, 0x200
	s_cselect_b32 s22, 6, 5
	v_lshlrev_b32_e32 v148, 15, v1
	v_or_b32_e32 v148, v148, v16
	v_or_b32_e32 v149, 0, v25
	v_lshlrev_b32_e32 v149, 12, v149
	v_or_b32_e32 v149, v149, v18
	v_or_b32_e32 v150, 8, v25
	v_lshlrev_b32_e32 v150, 12, v150
	v_or_b32_e32 v150, v150, v18
	v_or_b32_e32 v151, 16, v25
	v_lshlrev_b32_e32 v151, 12, v151
	v_or_b32_e32 v151, v151, v18
	v_or_b32_e32 v152, 24, v25
	v_lshlrev_b32_e32 v152, 12, v152
	v_or_b32_e32 v152, v152, v18
	v_readlane_b32 s12, v253, 31
	v_readlane_b32 s13, v253, 32
	v_readlane_b32 s16, v253, 29
	v_readlane_b32 s17, v253, 30
	s_lshr_b32 s29, s24, 8
	s_and_b32 s30, s24, 0xff
	s_add_u32 s12, s12, 0xc000000
	s_addc_u32 s13, s13, 0
	s_lshl_b32 s31, s29, 21
	s_add_u32 s12, s12, s31
	s_addc_u32 s13, s13, 0
	s_lshl_b32 s31, s30, 7
	s_add_u32 s12, s12, s31
	s_addc_u32 s13, s13, 0
	s_add_u32 s16, s16, 0x6000
	s_addc_u32 s17, s17, 0
	s_lshl_b32 s31, s29, 8
	s_add_u32 s16, s16, s31
	s_addc_u32 s17, s17, 0
	s_add_u32 s14, s94, 0x7000000
	s_addc_u32 s15, s95, 0
	s_lshl_b32 s31, s30, 17
	s_add_u32 s14, s14, s31
	s_addc_u32 s15, s15, 0
	s_lshl_b32 s31, s29, 7
	s_add_u32 s14, s14, s31
	s_addc_u32 s15, s15, 0
	s_mov_b32 s20, 0
	s_mov_b64 s[18:19], s[12:13]
	global_load_dword v100, v148, s[18:19]
	s_add_u32 s18, s18, 0x10000
	s_addc_u32 s19, s19, 0
	global_load_dword v101, v148, s[18:19]
	s_add_u32 s18, s18, 0x10000
	s_addc_u32 s19, s19, 0
	global_load_dword v102, v148, s[18:19]
	s_add_u32 s18, s18, 0x10000
	s_addc_u32 s19, s19, 0
	global_load_dword v103, v148, s[18:19]
	s_add_u32 s18, s18, 0x10000
	s_addc_u32 s19, s19, 0
	global_load_dword v104, v148, s[18:19]
	s_add_u32 s18, s18, 0x10000
	s_addc_u32 s19, s19, 0
	global_load_dword v105, v148, s[18:19]
	s_add_u32 s18, s18, 0x10000
	s_addc_u32 s19, s19, 0
	global_load_dword v106, v148, s[18:19]
	s_add_u32 s18, s18, 0x10000
	s_addc_u32 s19, s19, 0
	global_load_dword v107, v148, s[18:19]
	s_add_u32 s18, s18, 0x10000
	s_addc_u32 s19, s19, 0
	global_load_dword v108, v148, s[18:19]
	s_add_u32 s18, s18, 0x10000
	s_addc_u32 s19, s19, 0
	global_load_dword v109, v148, s[18:19]
	s_add_u32 s18, s18, 0x10000
	s_addc_u32 s19, s19, 0
	global_load_dword v110, v148, s[18:19]
	s_add_u32 s18, s18, 0x10000
	s_addc_u32 s19, s19, 0
	global_load_dword v111, v148, s[18:19]
	s_add_u32 s18, s18, 0x10000
	s_addc_u32 s19, s19, 0
	global_load_dword v112, v148, s[18:19]
	s_add_u32 s18, s18, 0x10000
	s_addc_u32 s19, s19, 0
	global_load_dword v113, v148, s[18:19]
	s_add_u32 s18, s18, 0x10000
	s_addc_u32 s19, s19, 0
	global_load_dword v114, v148, s[18:19]
	s_add_u32 s18, s18, 0x10000
	s_addc_u32 s19, s19, 0
	global_load_dword v115, v148, s[18:19]
	s_add_u32 s18, s18, 0x10000
	s_addc_u32 s19, s19, 0
	global_load_dword v116, v148, s[18:19]
	s_add_u32 s18, s18, 0x10000
	s_addc_u32 s19, s19, 0
	global_load_dword v117, v148, s[18:19]
	s_add_u32 s18, s18, 0x10000
	s_addc_u32 s19, s19, 0
	global_load_dword v118, v148, s[18:19]
	s_add_u32 s18, s18, 0x10000
	s_addc_u32 s19, s19, 0
	global_load_dword v119, v148, s[18:19]
	s_add_u32 s18, s18, 0x10000
	s_addc_u32 s19, s19, 0
	global_load_dword v120, v148, s[18:19]
	s_add_u32 s18, s18, 0x10000
	s_addc_u32 s19, s19, 0
	global_load_dword v121, v148, s[18:19]
	s_add_u32 s18, s18, 0x10000
	s_addc_u32 s19, s19, 0
	global_load_dword v122, v148, s[18:19]
	s_add_u32 s18, s18, 0x10000
	s_addc_u32 s19, s19, 0
	global_load_dword v123, v148, s[18:19]
	s_add_u32 s18, s18, 0x10000
	s_addc_u32 s19, s19, 0
	global_load_dword v124, v148, s[18:19]
	s_add_u32 s18, s18, 0x10000
	s_addc_u32 s19, s19, 0
	global_load_dword v125, v148, s[18:19]
	s_add_u32 s18, s18, 0x10000
	s_addc_u32 s19, s19, 0
	global_load_dword v126, v148, s[18:19]
	s_add_u32 s18, s18, 0x10000
	s_addc_u32 s19, s19, 0
	global_load_dword v127, v148, s[18:19]
	s_add_u32 s18, s18, 0x10000
	s_addc_u32 s19, s19, 0
	global_load_dword v128, v148, s[18:19]
	s_add_u32 s18, s18, 0x10000
	s_addc_u32 s19, s19, 0
	global_load_dword v129, v148, s[18:19]
	s_add_u32 s18, s18, 0x10000
	s_addc_u32 s19, s19, 0
	global_load_dword v130, v148, s[18:19]
	s_add_u32 s18, s18, 0x10000
	s_addc_u32 s19, s19, 0
	global_load_dword v131, v148, s[18:19]
	global_load_dwordx4 v[132:135], v20, s[16:17]
	global_load_dwordx4 v[136:139], v20, s[16:17] offset:16
	s_add_u32 s12, s12, 0xc00000
	s_addc_u32 s13, s13, 0
	s_add_u32 s16, s16, 0x600
	s_addc_u32 s17, s17, 0
.Lmy_dfw1_loop:
	s_add_i32 s21, s20, 1
	s_cmp_lt_u32 s21, s22
	s_cbranch_scc0 .Lmy_dfw1_elast
	s_mov_b64 s[18:19], s[12:13]
	global_load_dword v200, v148, s[18:19]
	s_add_u32 s18, s18, 0x10000
	s_addc_u32 s19, s19, 0
	global_load_dword v201, v148, s[18:19]
	s_add_u32 s18, s18, 0x10000
	s_addc_u32 s19, s19, 0
	global_load_dword v202, v148, s[18:19]
	s_add_u32 s18, s18, 0x10000
	s_addc_u32 s19, s19, 0
	global_load_dword v203, v148, s[18:19]
	s_add_u32 s18, s18, 0x10000
	s_addc_u32 s19, s19, 0
	global_load_dword v204, v148, s[18:19]
	s_add_u32 s18, s18, 0x10000
	s_addc_u32 s19, s19, 0
	global_load_dword v205, v148, s[18:19]
	s_add_u32 s18, s18, 0x10000
	s_addc_u32 s19, s19, 0
	global_load_dword v206, v148, s[18:19]
	s_add_u32 s18, s18, 0x10000
	s_addc_u32 s19, s19, 0
	global_load_dword v207, v148, s[18:19]
	s_add_u32 s18, s18, 0x10000
	s_addc_u32 s19, s19, 0
	global_load_dword v208, v148, s[18:19]
	s_add_u32 s18, s18, 0x10000
	s_addc_u32 s19, s19, 0
	global_load_dword v209, v148, s[18:19]
	s_add_u32 s18, s18, 0x10000
	s_addc_u32 s19, s19, 0
	global_load_dword v210, v148, s[18:19]
	s_add_u32 s18, s18, 0x10000
	s_addc_u32 s19, s19, 0
	global_load_dword v211, v148, s[18:19]
	s_add_u32 s18, s18, 0x10000
	s_addc_u32 s19, s19, 0
	global_load_dword v212, v148, s[18:19]
	s_add_u32 s18, s18, 0x10000
	s_addc_u32 s19, s19, 0
	global_load_dword v213, v148, s[18:19]
	s_add_u32 s18, s18, 0x10000
	s_addc_u32 s19, s19, 0
	global_load_dword v214, v148, s[18:19]
	s_add_u32 s18, s18, 0x10000
	s_addc_u32 s19, s19, 0
	global_load_dword v215, v148, s[18:19]
	s_add_u32 s18, s18, 0x10000
	s_addc_u32 s19, s19, 0
	global_load_dword v216, v148, s[18:19]
	s_add_u32 s18, s18, 0x10000
	s_addc_u32 s19, s19, 0
	global_load_dword v217, v148, s[18:19]
	s_add_u32 s18, s18, 0x10000
	s_addc_u32 s19, s19, 0
	global_load_dword v218, v148, s[18:19]
	s_add_u32 s18, s18, 0x10000
	s_addc_u32 s19, s19, 0
	global_load_dword v219, v148, s[18:19]
	s_add_u32 s18, s18, 0x10000
	s_addc_u32 s19, s19, 0
	global_load_dword v220, v148, s[18:19]
	s_add_u32 s18, s18, 0x10000
	s_addc_u32 s19, s19, 0
	global_load_dword v221, v148, s[18:19]
	s_add_u32 s18, s18, 0x10000
	s_addc_u32 s19, s19, 0
	global_load_dword v222, v148, s[18:19]
	s_add_u32 s18, s18, 0x10000
	s_addc_u32 s19, s19, 0
	global_load_dword v223, v148, s[18:19]
	s_add_u32 s18, s18, 0x10000
	s_addc_u32 s19, s19, 0
	global_load_dword v224, v148, s[18:19]
	s_add_u32 s18, s18, 0x10000
	s_addc_u32 s19, s19, 0
	global_load_dword v225, v148, s[18:19]
	s_add_u32 s18, s18, 0x10000
	s_addc_u32 s19, s19, 0
	global_load_dword v226, v148, s[18:19]
	s_add_u32 s18, s18, 0x10000
	s_addc_u32 s19, s19, 0
	global_load_dword v227, v148, s[18:19]
	s_add_u32 s18, s18, 0x10000
	s_addc_u32 s19, s19, 0
	global_load_dword v228, v148, s[18:19]
	s_add_u32 s18, s18, 0x10000
	s_addc_u32 s19, s19, 0
	global_load_dword v229, v148, s[18:19]
	s_add_u32 s18, s18, 0x10000
	s_addc_u32 s19, s19, 0
	global_load_dword v230, v148, s[18:19]
	s_add_u32 s18, s18, 0x10000
	s_addc_u32 s19, s19, 0
	global_load_dword v231, v148, s[18:19]
	global_load_dwordx4 v[140:143], v20, s[16:17]
	global_load_dwordx4 v[144:147], v20, s[16:17] offset:16
	s_add_u32 s12, s12, 0xc00000
	s_addc_u32 s13, s13, 0
	s_add_u32 s16, s16, 0x600
	s_addc_u32 s17, s17, 0
	s_waitcnt vmcnt(34)
	ds_write2_b32 v24, v100, v101 offset1:66
	ds_write2_b32 v24, v102, v103 offset0:132 offset1:198
	ds_write2_b32 v30, v104, v105 offset0:8 offset1:74
	ds_write2_b32 v30, v106, v107 offset0:140 offset1:206
	ds_write2_b32 v31, v108, v109 offset0:16 offset1:82
	ds_write2_b32 v31, v110, v111 offset0:148 offset1:214
	ds_write2_b32 v32, v112, v113 offset0:24 offset1:90
	ds_write2_b32 v32, v114, v115 offset0:156 offset1:222
	ds_write2_b32 v33, v116, v117 offset0:32 offset1:98
	ds_write2_b32 v33, v118, v119 offset0:164 offset1:230
	ds_write2_b32 v34, v120, v121 offset0:40 offset1:106
	ds_write2_b32 v34, v122, v123 offset0:172 offset1:238
	ds_write2_b32 v35, v124, v125 offset0:48 offset1:114
	ds_write2_b32 v35, v126, v127 offset0:180 offset1:246
	ds_write2_b32 v36, v128, v129 offset0:56 offset1:122
	ds_write2_b32 v36, v130, v131 offset0:188 offset1:254
	s_waitcnt lgkmcnt(0)
	ds_read_b32 v76, v26
	ds_read_b32 v77, v26 offset:132
	ds_read_b32 v78, v26 offset:264
	ds_read_b32 v79, v26 offset:396
	ds_read_b32 v80, v26 offset:528
	ds_read_b32 v81, v26 offset:660
	ds_read_b32 v82, v26 offset:792
	ds_read_b32 v83, v26 offset:924
	s_waitcnt lgkmcnt(0)
	v_pk_mul_f32 v[76:77], v[132:133], v[76:77]
	v_pk_mul_f32 v[78:79], v[134:135], v[78:79]
	v_pk_mul_f32 v[80:81], v[136:137], v[80:81]
	v_pk_mul_f32 v[82:83], v[138:139], v[82:83]
	v_cvt_pk_bf16_f32 v60, v76, v77
	v_cvt_pk_bf16_f32 v61, v78, v79
	v_cvt_pk_bf16_f32 v62, v80, v81
	v_cvt_pk_bf16_f32 v63, v82, v83
	global_store_dwordx4 v149, v[60:63], s[14:15]
	ds_read_b32 v76, v26 offset:32
	ds_read_b32 v77, v26 offset:164
	ds_read_b32 v78, v26 offset:296
	ds_read_b32 v79, v26 offset:428
	ds_read_b32 v80, v26 offset:560
	ds_read_b32 v81, v26 offset:692
	ds_read_b32 v82, v26 offset:824
	ds_read_b32 v83, v26 offset:956
	s_waitcnt lgkmcnt(0)
	v_pk_mul_f32 v[76:77], v[132:133], v[76:77]
	v_pk_mul_f32 v[78:79], v[134:135], v[78:79]
	v_pk_mul_f32 v[80:81], v[136:137], v[80:81]
	v_pk_mul_f32 v[82:83], v[138:139], v[82:83]
	v_cvt_pk_bf16_f32 v64, v76, v77
	v_cvt_pk_bf16_f32 v65, v78, v79
	v_cvt_pk_bf16_f32 v66, v80, v81
	v_cvt_pk_bf16_f32 v67, v82, v83
	global_store_dwordx4 v150, v[64:67], s[14:15]
	ds_read_b32 v76, v26 offset:64
	ds_read_b32 v77, v26 offset:196
	ds_read_b32 v78, v26 offset:328
	ds_read_b32 v79, v26 offset:460
	ds_read_b32 v80, v26 offset:592
	ds_read_b32 v81, v26 offset:724
	ds_read_b32 v82, v26 offset:856
	ds_read_b32 v83, v26 offset:988
	s_waitcnt lgkmcnt(0)
	v_pk_mul_f32 v[76:77], v[132:133], v[76:77]
	v_pk_mul_f32 v[78:79], v[134:135], v[78:79]
	v_pk_mul_f32 v[80:81], v[136:137], v[80:81]
	v_pk_mul_f32 v[82:83], v[138:139], v[82:83]
	v_cvt_pk_bf16_f32 v68, v76, v77
	v_cvt_pk_bf16_f32 v69, v78, v79
	v_cvt_pk_bf16_f32 v70, v80, v81
	v_cvt_pk_bf16_f32 v71, v82, v83
	global_store_dwordx4 v151, v[68:71], s[14:15]
	ds_read_b32 v76, v26 offset:96
	ds_read_b32 v77, v26 offset:228
	ds_read_b32 v78, v26 offset:360
	ds_read_b32 v79, v26 offset:492
	ds_read_b32 v80, v26 offset:624
	ds_read_b32 v81, v26 offset:756
	ds_read_b32 v82, v26 offset:888
	ds_read_b32 v83, v26 offset:1020
	s_waitcnt lgkmcnt(0)
	v_pk_mul_f32 v[76:77], v[132:133], v[76:77]
	v_pk_mul_f32 v[78:79], v[134:135], v[78:79]
	v_pk_mul_f32 v[80:81], v[136:137], v[80:81]
	v_pk_mul_f32 v[82:83], v[138:139], v[82:83]
	v_cvt_pk_bf16_f32 v72, v76, v77
	v_cvt_pk_bf16_f32 v73, v78, v79
	v_cvt_pk_bf16_f32 v74, v80, v81
	v_cvt_pk_bf16_f32 v75, v82, v83
	global_store_dwordx4 v152, v[72:75], s[14:15]
	s_add_i32 s20, s20, 1
	s_add_u32 s14, s14, 0x300
	s_addc_u32 s15, s15, 0
	s_add_i32 s21, s20, 1
	s_cmp_lt_u32 s21, s22
	s_cbranch_scc0 .Lmy_dfw1_olast
	s_mov_b64 s[18:19], s[12:13]
	global_load_dword v100, v148, s[18:19]
	s_add_u32 s18, s18, 0x10000
	s_addc_u32 s19, s19, 0
	global_load_dword v101, v148, s[18:19]
	s_add_u32 s18, s18, 0x10000
	s_addc_u32 s19, s19, 0
	global_load_dword v102, v148, s[18:19]
	s_add_u32 s18, s18, 0x10000
	s_addc_u32 s19, s19, 0
	global_load_dword v103, v148, s[18:19]
	s_add_u32 s18, s18, 0x10000
	s_addc_u32 s19, s19, 0
	global_load_dword v104, v148, s[18:19]
	s_add_u32 s18, s18, 0x10000
	s_addc_u32 s19, s19, 0
	global_load_dword v105, v148, s[18:19]
	s_add_u32 s18, s18, 0x10000
	s_addc_u32 s19, s19, 0
	global_load_dword v106, v148, s[18:19]
	s_add_u32 s18, s18, 0x10000
	s_addc_u32 s19, s19, 0
	global_load_dword v107, v148, s[18:19]
	s_add_u32 s18, s18, 0x10000
	s_addc_u32 s19, s19, 0
	global_load_dword v108, v148, s[18:19]
	s_add_u32 s18, s18, 0x10000
	s_addc_u32 s19, s19, 0
	global_load_dword v109, v148, s[18:19]
	s_add_u32 s18, s18, 0x10000
	s_addc_u32 s19, s19, 0
	global_load_dword v110, v148, s[18:19]
	s_add_u32 s18, s18, 0x10000
	s_addc_u32 s19, s19, 0
	global_load_dword v111, v148, s[18:19]
	s_add_u32 s18, s18, 0x10000
	s_addc_u32 s19, s19, 0
	global_load_dword v112, v148, s[18:19]
	s_add_u32 s18, s18, 0x10000
	s_addc_u32 s19, s19, 0
	global_load_dword v113, v148, s[18:19]
	s_add_u32 s18, s18, 0x10000
	s_addc_u32 s19, s19, 0
	global_load_dword v114, v148, s[18:19]
	s_add_u32 s18, s18, 0x10000
	s_addc_u32 s19, s19, 0
	global_load_dword v115, v148, s[18:19]
	s_add_u32 s18, s18, 0x10000
	s_addc_u32 s19, s19, 0
	global_load_dword v116, v148, s[18:19]
	s_add_u32 s18, s18, 0x10000
	s_addc_u32 s19, s19, 0
	global_load_dword v117, v148, s[18:19]
	s_add_u32 s18, s18, 0x10000
	s_addc_u32 s19, s19, 0
	global_load_dword v118, v148, s[18:19]
	s_add_u32 s18, s18, 0x10000
	s_addc_u32 s19, s19, 0
	global_load_dword v119, v148, s[18:19]
	s_add_u32 s18, s18, 0x10000
	s_addc_u32 s19, s19, 0
	global_load_dword v120, v148, s[18:19]
	s_add_u32 s18, s18, 0x10000
	s_addc_u32 s19, s19, 0
	global_load_dword v121, v148, s[18:19]
	s_add_u32 s18, s18, 0x10000
	s_addc_u32 s19, s19, 0
	global_load_dword v122, v148, s[18:19]
	s_add_u32 s18, s18, 0x10000
	s_addc_u32 s19, s19, 0
	global_load_dword v123, v148, s[18:19]
	s_add_u32 s18, s18, 0x10000
	s_addc_u32 s19, s19, 0
	global_load_dword v124, v148, s[18:19]
	s_add_u32 s18, s18, 0x10000
	s_addc_u32 s19, s19, 0
	global_load_dword v125, v148, s[18:19]
	s_add_u32 s18, s18, 0x10000
	s_addc_u32 s19, s19, 0
	global_load_dword v126, v148, s[18:19]
	s_add_u32 s18, s18, 0x10000
	s_addc_u32 s19, s19, 0
	global_load_dword v127, v148, s[18:19]
	s_add_u32 s18, s18, 0x10000
	s_addc_u32 s19, s19, 0
	global_load_dword v128, v148, s[18:19]
	s_add_u32 s18, s18, 0x10000
	s_addc_u32 s19, s19, 0
	global_load_dword v129, v148, s[18:19]
	s_add_u32 s18, s18, 0x10000
	s_addc_u32 s19, s19, 0
	global_load_dword v130, v148, s[18:19]
	s_add_u32 s18, s18, 0x10000
	s_addc_u32 s19, s19, 0
	global_load_dword v131, v148, s[18:19]
	global_load_dwordx4 v[132:135], v20, s[16:17]
	global_load_dwordx4 v[136:139], v20, s[16:17] offset:16
	s_add_u32 s12, s12, 0xc00000
	s_addc_u32 s13, s13, 0
	s_add_u32 s16, s16, 0x600
	s_addc_u32 s17, s17, 0
	s_waitcnt vmcnt(34)
	ds_write2_b32 v24, v200, v201 offset1:66
	ds_write2_b32 v24, v202, v203 offset0:132 offset1:198
	ds_write2_b32 v30, v204, v205 offset0:8 offset1:74
	ds_write2_b32 v30, v206, v207 offset0:140 offset1:206
	ds_write2_b32 v31, v208, v209 offset0:16 offset1:82
	ds_write2_b32 v31, v210, v211 offset0:148 offset1:214
	ds_write2_b32 v32, v212, v213 offset0:24 offset1:90
	ds_write2_b32 v32, v214, v215 offset0:156 offset1:222
	ds_write2_b32 v33, v216, v217 offset0:32 offset1:98
	ds_write2_b32 v33, v218, v219 offset0:164 offset1:230
	ds_write2_b32 v34, v220, v221 offset0:40 offset1:106
	ds_write2_b32 v34, v222, v223 offset0:172 offset1:238
	ds_write2_b32 v35, v224, v225 offset0:48 offset1:114
	ds_write2_b32 v35, v226, v227 offset0:180 offset1:246
	ds_write2_b32 v36, v228, v229 offset0:56 offset1:122
	ds_write2_b32 v36, v230, v231 offset0:188 offset1:254
	s_waitcnt lgkmcnt(0)
	ds_read_b32 v76, v26
	ds_read_b32 v77, v26 offset:132
	ds_read_b32 v78, v26 offset:264
	ds_read_b32 v79, v26 offset:396
	ds_read_b32 v80, v26 offset:528
	ds_read_b32 v81, v26 offset:660
	ds_read_b32 v82, v26 offset:792
	ds_read_b32 v83, v26 offset:924
	s_waitcnt lgkmcnt(0)
	v_pk_mul_f32 v[76:77], v[140:141], v[76:77]
	v_pk_mul_f32 v[78:79], v[142:143], v[78:79]
	v_pk_mul_f32 v[80:81], v[144:145], v[80:81]
	v_pk_mul_f32 v[82:83], v[146:147], v[82:83]
	v_cvt_pk_bf16_f32 v60, v76, v77
	v_cvt_pk_bf16_f32 v61, v78, v79
	v_cvt_pk_bf16_f32 v62, v80, v81
	v_cvt_pk_bf16_f32 v63, v82, v83
	global_store_dwordx4 v149, v[60:63], s[14:15]
	ds_read_b32 v76, v26 offset:32
	ds_read_b32 v77, v26 offset:164
	ds_read_b32 v78, v26 offset:296
	ds_read_b32 v79, v26 offset:428
	ds_read_b32 v80, v26 offset:560
	ds_read_b32 v81, v26 offset:692
	ds_read_b32 v82, v26 offset:824
	ds_read_b32 v83, v26 offset:956
	s_waitcnt lgkmcnt(0)
	v_pk_mul_f32 v[76:77], v[140:141], v[76:77]
	v_pk_mul_f32 v[78:79], v[142:143], v[78:79]
	v_pk_mul_f32 v[80:81], v[144:145], v[80:81]
	v_pk_mul_f32 v[82:83], v[146:147], v[82:83]
	v_cvt_pk_bf16_f32 v64, v76, v77
	v_cvt_pk_bf16_f32 v65, v78, v79
	v_cvt_pk_bf16_f32 v66, v80, v81
	v_cvt_pk_bf16_f32 v67, v82, v83
	global_store_dwordx4 v150, v[64:67], s[14:15]
	ds_read_b32 v76, v26 offset:64
	ds_read_b32 v77, v26 offset:196
	ds_read_b32 v78, v26 offset:328
	ds_read_b32 v79, v26 offset:460
	ds_read_b32 v80, v26 offset:592
	ds_read_b32 v81, v26 offset:724
	ds_read_b32 v82, v26 offset:856
	ds_read_b32 v83, v26 offset:988
	s_waitcnt lgkmcnt(0)
	v_pk_mul_f32 v[76:77], v[140:141], v[76:77]
	v_pk_mul_f32 v[78:79], v[142:143], v[78:79]
	v_pk_mul_f32 v[80:81], v[144:145], v[80:81]
	v_pk_mul_f32 v[82:83], v[146:147], v[82:83]
	v_cvt_pk_bf16_f32 v68, v76, v77
	v_cvt_pk_bf16_f32 v69, v78, v79
	v_cvt_pk_bf16_f32 v70, v80, v81
	v_cvt_pk_bf16_f32 v71, v82, v83
	global_store_dwordx4 v151, v[68:71], s[14:15]
	ds_read_b32 v76, v26 offset:96
	ds_read_b32 v77, v26 offset:228
	ds_read_b32 v78, v26 offset:360
	ds_read_b32 v79, v26 offset:492
	ds_read_b32 v80, v26 offset:624
	ds_read_b32 v81, v26 offset:756
	ds_read_b32 v82, v26 offset:888
	ds_read_b32 v83, v26 offset:1020
	s_waitcnt lgkmcnt(0)
	v_pk_mul_f32 v[76:77], v[140:141], v[76:77]
	v_pk_mul_f32 v[78:79], v[142:143], v[78:79]
	v_pk_mul_f32 v[80:81], v[144:145], v[80:81]
	v_pk_mul_f32 v[82:83], v[146:147], v[82:83]
	v_cvt_pk_bf16_f32 v72, v76, v77
	v_cvt_pk_bf16_f32 v73, v78, v79
	v_cvt_pk_bf16_f32 v74, v80, v81
	v_cvt_pk_bf16_f32 v75, v82, v83
	global_store_dwordx4 v152, v[72:75], s[14:15]
	s_add_i32 s20, s20, 1
	s_add_u32 s14, s14, 0x300
	s_addc_u32 s15, s15, 0
	s_branch .Lmy_dfw1_loop
.Lmy_dfw1_elast:
	s_waitcnt vmcnt(0)
	ds_write2_b32 v24, v100, v101 offset1:66
	ds_write2_b32 v24, v102, v103 offset0:132 offset1:198
	ds_write2_b32 v30, v104, v105 offset0:8 offset1:74
	ds_write2_b32 v30, v106, v107 offset0:140 offset1:206
	ds_write2_b32 v31, v108, v109 offset0:16 offset1:82
	ds_write2_b32 v31, v110, v111 offset0:148 offset1:214
	ds_write2_b32 v32, v112, v113 offset0:24 offset1:90
	ds_write2_b32 v32, v114, v115 offset0:156 offset1:222
	ds_write2_b32 v33, v116, v117 offset0:32 offset1:98
	ds_write2_b32 v33, v118, v119 offset0:164 offset1:230
	ds_write2_b32 v34, v120, v121 offset0:40 offset1:106
	ds_write2_b32 v34, v122, v123 offset0:172 offset1:238
	ds_write2_b32 v35, v124, v125 offset0:48 offset1:114
	ds_write2_b32 v35, v126, v127 offset0:180 offset1:246
	ds_write2_b32 v36, v128, v129 offset0:56 offset1:122
	ds_write2_b32 v36, v130, v131 offset0:188 offset1:254
	s_waitcnt lgkmcnt(0)
	ds_read_b32 v76, v26
	ds_read_b32 v77, v26 offset:132
	ds_read_b32 v78, v26 offset:264
	ds_read_b32 v79, v26 offset:396
	ds_read_b32 v80, v26 offset:528
	ds_read_b32 v81, v26 offset:660
	ds_read_b32 v82, v26 offset:792
	ds_read_b32 v83, v26 offset:924
	s_waitcnt lgkmcnt(0)
	v_pk_mul_f32 v[76:77], v[132:133], v[76:77]
	v_pk_mul_f32 v[78:79], v[134:135], v[78:79]
	v_pk_mul_f32 v[80:81], v[136:137], v[80:81]
	v_pk_mul_f32 v[82:83], v[138:139], v[82:83]
	v_cvt_pk_bf16_f32 v60, v76, v77
	v_cvt_pk_bf16_f32 v61, v78, v79
	v_cvt_pk_bf16_f32 v62, v80, v81
	v_cvt_pk_bf16_f32 v63, v82, v83
	global_store_dwordx4 v149, v[60:63], s[14:15]
	ds_read_b32 v76, v26 offset:32
	ds_read_b32 v77, v26 offset:164
	ds_read_b32 v78, v26 offset:296
	ds_read_b32 v79, v26 offset:428
	ds_read_b32 v80, v26 offset:560
	ds_read_b32 v81, v26 offset:692
	ds_read_b32 v82, v26 offset:824
	ds_read_b32 v83, v26 offset:956
	s_waitcnt lgkmcnt(0)
	v_pk_mul_f32 v[76:77], v[132:133], v[76:77]
	v_pk_mul_f32 v[78:79], v[134:135], v[78:79]
	v_pk_mul_f32 v[80:81], v[136:137], v[80:81]
	v_pk_mul_f32 v[82:83], v[138:139], v[82:83]
	v_cvt_pk_bf16_f32 v64, v76, v77
	v_cvt_pk_bf16_f32 v65, v78, v79
	v_cvt_pk_bf16_f32 v66, v80, v81
	v_cvt_pk_bf16_f32 v67, v82, v83
	global_store_dwordx4 v150, v[64:67], s[14:15]
	ds_read_b32 v76, v26 offset:64
	ds_read_b32 v77, v26 offset:196
	ds_read_b32 v78, v26 offset:328
	ds_read_b32 v79, v26 offset:460
	ds_read_b32 v80, v26 offset:592
	ds_read_b32 v81, v26 offset:724
	ds_read_b32 v82, v26 offset:856
	ds_read_b32 v83, v26 offset:988
	s_waitcnt lgkmcnt(0)
	v_pk_mul_f32 v[76:77], v[132:133], v[76:77]
	v_pk_mul_f32 v[78:79], v[134:135], v[78:79]
	v_pk_mul_f32 v[80:81], v[136:137], v[80:81]
	v_pk_mul_f32 v[82:83], v[138:139], v[82:83]
	v_cvt_pk_bf16_f32 v68, v76, v77
	v_cvt_pk_bf16_f32 v69, v78, v79
	v_cvt_pk_bf16_f32 v70, v80, v81
	v_cvt_pk_bf16_f32 v71, v82, v83
	global_store_dwordx4 v151, v[68:71], s[14:15]
	ds_read_b32 v76, v26 offset:96
	ds_read_b32 v77, v26 offset:228
	ds_read_b32 v78, v26 offset:360
	ds_read_b32 v79, v26 offset:492
	ds_read_b32 v80, v26 offset:624
	ds_read_b32 v81, v26 offset:756
	ds_read_b32 v82, v26 offset:888
	ds_read_b32 v83, v26 offset:1020
	s_waitcnt lgkmcnt(0)
	v_pk_mul_f32 v[76:77], v[132:133], v[76:77]
	v_pk_mul_f32 v[78:79], v[134:135], v[78:79]
	v_pk_mul_f32 v[80:81], v[136:137], v[80:81]
	v_pk_mul_f32 v[82:83], v[138:139], v[82:83]
	v_cvt_pk_bf16_f32 v72, v76, v77
	v_cvt_pk_bf16_f32 v73, v78, v79
	v_cvt_pk_bf16_f32 v74, v80, v81
	v_cvt_pk_bf16_f32 v75, v82, v83
	global_store_dwordx4 v152, v[72:75], s[14:15]
	s_add_i32 s20, s20, 1
	s_add_u32 s14, s14, 0x300
	s_addc_u32 s15, s15, 0
	s_branch .Lmy_dfw1_done
.Lmy_dfw1_olast:
	s_waitcnt vmcnt(0)
	ds_write2_b32 v24, v200, v201 offset1:66
	ds_write2_b32 v24, v202, v203 offset0:132 offset1:198
	ds_write2_b32 v30, v204, v205 offset0:8 offset1:74
	ds_write2_b32 v30, v206, v207 offset0:140 offset1:206
	ds_write2_b32 v31, v208, v209 offset0:16 offset1:82
	ds_write2_b32 v31, v210, v211 offset0:148 offset1:214
	ds_write2_b32 v32, v212, v213 offset0:24 offset1:90
	ds_write2_b32 v32, v214, v215 offset0:156 offset1:222
	ds_write2_b32 v33, v216, v217 offset0:32 offset1:98
	ds_write2_b32 v33, v218, v219 offset0:164 offset1:230
	ds_write2_b32 v34, v220, v221 offset0:40 offset1:106
	ds_write2_b32 v34, v222, v223 offset0:172 offset1:238
	ds_write2_b32 v35, v224, v225 offset0:48 offset1:114
	ds_write2_b32 v35, v226, v227 offset0:180 offset1:246
	ds_write2_b32 v36, v228, v229 offset0:56 offset1:122
	ds_write2_b32 v36, v230, v231 offset0:188 offset1:254
	s_waitcnt lgkmcnt(0)
	ds_read_b32 v76, v26
	ds_read_b32 v77, v26 offset:132
	ds_read_b32 v78, v26 offset:264
	ds_read_b32 v79, v26 offset:396
	ds_read_b32 v80, v26 offset:528
	ds_read_b32 v81, v26 offset:660
	ds_read_b32 v82, v26 offset:792
	ds_read_b32 v83, v26 offset:924
	s_waitcnt lgkmcnt(0)
	v_pk_mul_f32 v[76:77], v[140:141], v[76:77]
	v_pk_mul_f32 v[78:79], v[142:143], v[78:79]
	v_pk_mul_f32 v[80:81], v[144:145], v[80:81]
	v_pk_mul_f32 v[82:83], v[146:147], v[82:83]
	v_cvt_pk_bf16_f32 v60, v76, v77
	v_cvt_pk_bf16_f32 v61, v78, v79
	v_cvt_pk_bf16_f32 v62, v80, v81
	v_cvt_pk_bf16_f32 v63, v82, v83
	global_store_dwordx4 v149, v[60:63], s[14:15]
	ds_read_b32 v76, v26 offset:32
	ds_read_b32 v77, v26 offset:164
	ds_read_b32 v78, v26 offset:296
	ds_read_b32 v79, v26 offset:428
	ds_read_b32 v80, v26 offset:560
	ds_read_b32 v81, v26 offset:692
	ds_read_b32 v82, v26 offset:824
	ds_read_b32 v83, v26 offset:956
	s_waitcnt lgkmcnt(0)
	v_pk_mul_f32 v[76:77], v[140:141], v[76:77]
	v_pk_mul_f32 v[78:79], v[142:143], v[78:79]
	v_pk_mul_f32 v[80:81], v[144:145], v[80:81]
	v_pk_mul_f32 v[82:83], v[146:147], v[82:83]
	v_cvt_pk_bf16_f32 v64, v76, v77
	v_cvt_pk_bf16_f32 v65, v78, v79
	v_cvt_pk_bf16_f32 v66, v80, v81
	v_cvt_pk_bf16_f32 v67, v82, v83
	global_store_dwordx4 v150, v[64:67], s[14:15]
	ds_read_b32 v76, v26 offset:64
	ds_read_b32 v77, v26 offset:196
	ds_read_b32 v78, v26 offset:328
	ds_read_b32 v79, v26 offset:460
	ds_read_b32 v80, v26 offset:592
	ds_read_b32 v81, v26 offset:724
	ds_read_b32 v82, v26 offset:856
	ds_read_b32 v83, v26 offset:988
	s_waitcnt lgkmcnt(0)
	v_pk_mul_f32 v[76:77], v[140:141], v[76:77]
	v_pk_mul_f32 v[78:79], v[142:143], v[78:79]
	v_pk_mul_f32 v[80:81], v[144:145], v[80:81]
	v_pk_mul_f32 v[82:83], v[146:147], v[82:83]
	v_cvt_pk_bf16_f32 v68, v76, v77
	v_cvt_pk_bf16_f32 v69, v78, v79
	v_cvt_pk_bf16_f32 v70, v80, v81
	v_cvt_pk_bf16_f32 v71, v82, v83
	global_store_dwordx4 v151, v[68:71], s[14:15]
	ds_read_b32 v76, v26 offset:96
	ds_read_b32 v77, v26 offset:228
	ds_read_b32 v78, v26 offset:360
	ds_read_b32 v79, v26 offset:492
	ds_read_b32 v80, v26 offset:624
	ds_read_b32 v81, v26 offset:756
	ds_read_b32 v82, v26 offset:888
	ds_read_b32 v83, v26 offset:1020
	s_waitcnt lgkmcnt(0)
	v_pk_mul_f32 v[76:77], v[140:141], v[76:77]
	v_pk_mul_f32 v[78:79], v[142:143], v[78:79]
	v_pk_mul_f32 v[80:81], v[144:145], v[80:81]
	v_pk_mul_f32 v[82:83], v[146:147], v[82:83]
	v_cvt_pk_bf16_f32 v72, v76, v77
	v_cvt_pk_bf16_f32 v73, v78, v79
	v_cvt_pk_bf16_f32 v74, v80, v81
	v_cvt_pk_bf16_f32 v75, v82, v83
	global_store_dwordx4 v152, v[72:75], s[14:15]
	s_add_i32 s20, s20, 1
	s_add_u32 s14, s14, 0x300
	s_addc_u32 s15, s15, 0
.Lmy_dfw1_done:
	v_lshlrev_b32_e32 v148, 13, v1
	v_or_b32_e32 v148, v148, v16
	v_or_b32_e32 v149, 0, v25
	v_lshlrev_b32_e32 v149, 14, v149
	v_or_b32_e32 v149, v149, v18
	v_or_b32_e32 v150, 8, v25
	v_lshlrev_b32_e32 v150, 14, v150
	v_or_b32_e32 v150, v150, v18
	v_or_b32_e32 v151, 16, v25
	v_lshlrev_b32_e32 v151, 14, v151
	v_or_b32_e32 v151, v151, v18
	v_or_b32_e32 v152, 24, v25
	v_lshlrev_b32_e32 v152, 14, v152
	v_or_b32_e32 v152, v152, v18
	v_readlane_b32 s12, v253, 33
	v_readlane_b32 s13, v253, 34
	s_lshr_b32 s29, s24, 6
	s_and_b32 s30, s24, 63
	s_add_u32 s12, s12, 0xc000000
	s_addc_u32 s13, s13, 0
	s_lshl_b32 s31, s29, 19
	s_add_u32 s12, s12, s31
	s_addc_u32 s13, s13, 0
	s_lshl_b32 s31, s30, 7
	s_add_u32 s12, s12, s31
	s_addc_u32 s13, s13, 0
	s_add_u32 s14, s94, 0xf000000
	s_addc_u32 s15, s95, 0
	s_lshl_b32 s31, s30, 19
	s_add_u32 s14, s14, s31
	s_addc_u32 s15, s15, 0
	s_lshl_b32 s31, s29, 7
	s_add_u32 s14, s14, s31
	s_addc_u32 s15, s15, 0
	s_mov_b32 s20, 0
	s_mov_b64 s[18:19], s[12:13]
	global_load_dword v100, v148, s[18:19]
	s_add_u32 s18, s18, 0x4000
	s_addc_u32 s19, s19, 0
	global_load_dword v101, v148, s[18:19]
	s_add_u32 s18, s18, 0x4000
	s_addc_u32 s19, s19, 0
	global_load_dword v102, v148, s[18:19]
	s_add_u32 s18, s18, 0x4000
	s_addc_u32 s19, s19, 0
	global_load_dword v103, v148, s[18:19]
	s_add_u32 s18, s18, 0x4000
	s_addc_u32 s19, s19, 0
	global_load_dword v104, v148, s[18:19]
	s_add_u32 s18, s18, 0x4000
	s_addc_u32 s19, s19, 0
	global_load_dword v105, v148, s[18:19]
	s_add_u32 s18, s18, 0x4000
	s_addc_u32 s19, s19, 0
	global_load_dword v106, v148, s[18:19]
	s_add_u32 s18, s18, 0x4000
	s_addc_u32 s19, s19, 0
	global_load_dword v107, v148, s[18:19]
	s_add_u32 s18, s18, 0x4000
	s_addc_u32 s19, s19, 0
	global_load_dword v108, v148, s[18:19]
	s_add_u32 s18, s18, 0x4000
	s_addc_u32 s19, s19, 0
	global_load_dword v109, v148, s[18:19]
	s_add_u32 s18, s18, 0x4000
	s_addc_u32 s19, s19, 0
	global_load_dword v110, v148, s[18:19]
	s_add_u32 s18, s18, 0x4000
	s_addc_u32 s19, s19, 0
	global_load_dword v111, v148, s[18:19]
	s_add_u32 s18, s18, 0x4000
	s_addc_u32 s19, s19, 0
	global_load_dword v112, v148, s[18:19]
	s_add_u32 s18, s18, 0x4000
	s_addc_u32 s19, s19, 0
	global_load_dword v113, v148, s[18:19]
	s_add_u32 s18, s18, 0x4000
	s_addc_u32 s19, s19, 0
	global_load_dword v114, v148, s[18:19]
	s_add_u32 s18, s18, 0x4000
	s_addc_u32 s19, s19, 0
	global_load_dword v115, v148, s[18:19]
	s_add_u32 s18, s18, 0x4000
	s_addc_u32 s19, s19, 0
	global_load_dword v116, v148, s[18:19]
	s_add_u32 s18, s18, 0x4000
	s_addc_u32 s19, s19, 0
	global_load_dword v117, v148, s[18:19]
	s_add_u32 s18, s18, 0x4000
	s_addc_u32 s19, s19, 0
	global_load_dword v118, v148, s[18:19]
	s_add_u32 s18, s18, 0x4000
	s_addc_u32 s19, s19, 0
	global_load_dword v119, v148, s[18:19]
	s_add_u32 s18, s18, 0x4000
	s_addc_u32 s19, s19, 0
	global_load_dword v120, v148, s[18:19]
	s_add_u32 s18, s18, 0x4000
	s_addc_u32 s19, s19, 0
	global_load_dword v121, v148, s[18:19]
	s_add_u32 s18, s18, 0x4000
	s_addc_u32 s19, s19, 0
	global_load_dword v122, v148, s[18:19]
	s_add_u32 s18, s18, 0x4000
	s_addc_u32 s19, s19, 0
	global_load_dword v123, v148, s[18:19]
	s_add_u32 s18, s18, 0x4000
	s_addc_u32 s19, s19, 0
	global_load_dword v124, v148, s[18:19]
	s_add_u32 s18, s18, 0x4000
	s_addc_u32 s19, s19, 0
	global_load_dword v125, v148, s[18:19]
	s_add_u32 s18, s18, 0x4000
	s_addc_u32 s19, s19, 0
	global_load_dword v126, v148, s[18:19]
	s_add_u32 s18, s18, 0x4000
	s_addc_u32 s19, s19, 0
	global_load_dword v127, v148, s[18:19]
	s_add_u32 s18, s18, 0x4000
	s_addc_u32 s19, s19, 0
	global_load_dword v128, v148, s[18:19]
	s_add_u32 s18, s18, 0x4000
	s_addc_u32 s19, s19, 0
	global_load_dword v129, v148, s[18:19]
	s_add_u32 s18, s18, 0x4000
	s_addc_u32 s19, s19, 0
	global_load_dword v130, v148, s[18:19]
	s_add_u32 s18, s18, 0x4000
	s_addc_u32 s19, s19, 0
	global_load_dword v131, v148, s[18:19]
	s_add_u32 s12, s12, 0xc00000
	s_addc_u32 s13, s13, 0
.Lmy_dfw2_loop:
	s_add_i32 s21, s20, 1
	s_cmp_lt_u32 s21, s22
	s_cbranch_scc0 .Lmy_dfw2_elast
	s_mov_b64 s[18:19], s[12:13]
	global_load_dword v200, v148, s[18:19]
	s_add_u32 s18, s18, 0x4000
	s_addc_u32 s19, s19, 0
	global_load_dword v201, v148, s[18:19]
	s_add_u32 s18, s18, 0x4000
	s_addc_u32 s19, s19, 0
	global_load_dword v202, v148, s[18:19]
	s_add_u32 s18, s18, 0x4000
	s_addc_u32 s19, s19, 0
	global_load_dword v203, v148, s[18:19]
	s_add_u32 s18, s18, 0x4000
	s_addc_u32 s19, s19, 0
	global_load_dword v204, v148, s[18:19]
	s_add_u32 s18, s18, 0x4000
	s_addc_u32 s19, s19, 0
	global_load_dword v205, v148, s[18:19]
	s_add_u32 s18, s18, 0x4000
	s_addc_u32 s19, s19, 0
	global_load_dword v206, v148, s[18:19]
	s_add_u32 s18, s18, 0x4000
	s_addc_u32 s19, s19, 0
	global_load_dword v207, v148, s[18:19]
	s_add_u32 s18, s18, 0x4000
	s_addc_u32 s19, s19, 0
	global_load_dword v208, v148, s[18:19]
	s_add_u32 s18, s18, 0x4000
	s_addc_u32 s19, s19, 0
	global_load_dword v209, v148, s[18:19]
	s_add_u32 s18, s18, 0x4000
	s_addc_u32 s19, s19, 0
	global_load_dword v210, v148, s[18:19]
	s_add_u32 s18, s18, 0x4000
	s_addc_u32 s19, s19, 0
	global_load_dword v211, v148, s[18:19]
	s_add_u32 s18, s18, 0x4000
	s_addc_u32 s19, s19, 0
	global_load_dword v212, v148, s[18:19]
	s_add_u32 s18, s18, 0x4000
	s_addc_u32 s19, s19, 0
	global_load_dword v213, v148, s[18:19]
	s_add_u32 s18, s18, 0x4000
	s_addc_u32 s19, s19, 0
	global_load_dword v214, v148, s[18:19]
	s_add_u32 s18, s18, 0x4000
	s_addc_u32 s19, s19, 0
	global_load_dword v215, v148, s[18:19]
	s_add_u32 s18, s18, 0x4000
	s_addc_u32 s19, s19, 0
	global_load_dword v216, v148, s[18:19]
	s_add_u32 s18, s18, 0x4000
	s_addc_u32 s19, s19, 0
	global_load_dword v217, v148, s[18:19]
	s_add_u32 s18, s18, 0x4000
	s_addc_u32 s19, s19, 0
	global_load_dword v218, v148, s[18:19]
	s_add_u32 s18, s18, 0x4000
	s_addc_u32 s19, s19, 0
	global_load_dword v219, v148, s[18:19]
	s_add_u32 s18, s18, 0x4000
	s_addc_u32 s19, s19, 0
	global_load_dword v220, v148, s[18:19]
	s_add_u32 s18, s18, 0x4000
	s_addc_u32 s19, s19, 0
	global_load_dword v221, v148, s[18:19]
	s_add_u32 s18, s18, 0x4000
	s_addc_u32 s19, s19, 0
	global_load_dword v222, v148, s[18:19]
	s_add_u32 s18, s18, 0x4000
	s_addc_u32 s19, s19, 0
	global_load_dword v223, v148, s[18:19]
	s_add_u32 s18, s18, 0x4000
	s_addc_u32 s19, s19, 0
	global_load_dword v224, v148, s[18:19]
	s_add_u32 s18, s18, 0x4000
	s_addc_u32 s19, s19, 0
	global_load_dword v225, v148, s[18:19]
	s_add_u32 s18, s18, 0x4000
	s_addc_u32 s19, s19, 0
	global_load_dword v226, v148, s[18:19]
	s_add_u32 s18, s18, 0x4000
	s_addc_u32 s19, s19, 0
	global_load_dword v227, v148, s[18:19]
	s_add_u32 s18, s18, 0x4000
	s_addc_u32 s19, s19, 0
	global_load_dword v228, v148, s[18:19]
	s_add_u32 s18, s18, 0x4000
	s_addc_u32 s19, s19, 0
	global_load_dword v229, v148, s[18:19]
	s_add_u32 s18, s18, 0x4000
	s_addc_u32 s19, s19, 0
	global_load_dword v230, v148, s[18:19]
	s_add_u32 s18, s18, 0x4000
	s_addc_u32 s19, s19, 0
	global_load_dword v231, v148, s[18:19]
	s_add_u32 s12, s12, 0xc00000
	s_addc_u32 s13, s13, 0
	s_waitcnt vmcnt(32)
	ds_write2_b32 v24, v100, v101 offset1:66
	ds_write2_b32 v24, v102, v103 offset0:132 offset1:198
	ds_write2_b32 v30, v104, v105 offset0:8 offset1:74
	ds_write2_b32 v30, v106, v107 offset0:140 offset1:206
	ds_write2_b32 v31, v108, v109 offset0:16 offset1:82
	ds_write2_b32 v31, v110, v111 offset0:148 offset1:214
	ds_write2_b32 v32, v112, v113 offset0:24 offset1:90
	ds_write2_b32 v32, v114, v115 offset0:156 offset1:222
	ds_write2_b32 v33, v116, v117 offset0:32 offset1:98
	ds_write2_b32 v33, v118, v119 offset0:164 offset1:230
	ds_write2_b32 v34, v120, v121 offset0:40 offset1:106
	ds_write2_b32 v34, v122, v123 offset0:172 offset1:238
	ds_write2_b32 v35, v124, v125 offset0:48 offset1:114
	ds_write2_b32 v35, v126, v127 offset0:180 offset1:246
	ds_write2_b32 v36, v128, v129 offset0:56 offset1:122
	ds_write2_b32 v36, v130, v131 offset0:188 offset1:254
	s_waitcnt lgkmcnt(0)
	ds_read_b32 v76, v26
	ds_read_b32 v77, v26 offset:132
	ds_read_b32 v78, v26 offset:264
	ds_read_b32 v79, v26 offset:396
	ds_read_b32 v80, v26 offset:528
	ds_read_b32 v81, v26 offset:660
	ds_read_b32 v82, v26 offset:792
	ds_read_b32 v83, v26 offset:924
	s_waitcnt lgkmcnt(0)
	v_cvt_pk_bf16_f32 v60, v76, v77
	v_cvt_pk_bf16_f32 v61, v78, v79
	v_cvt_pk_bf16_f32 v62, v80, v81
	v_cvt_pk_bf16_f32 v63, v82, v83
	global_store_dwordx4 v149, v[60:63], s[14:15]
	ds_read_b32 v76, v26 offset:32
	ds_read_b32 v77, v26 offset:164
	ds_read_b32 v78, v26 offset:296
	ds_read_b32 v79, v26 offset:428
	ds_read_b32 v80, v26 offset:560
	ds_read_b32 v81, v26 offset:692
	ds_read_b32 v82, v26 offset:824
	ds_read_b32 v83, v26 offset:956
	s_waitcnt lgkmcnt(0)
	v_cvt_pk_bf16_f32 v64, v76, v77
	v_cvt_pk_bf16_f32 v65, v78, v79
	v_cvt_pk_bf16_f32 v66, v80, v81
	v_cvt_pk_bf16_f32 v67, v82, v83
	global_store_dwordx4 v150, v[64:67], s[14:15]
	ds_read_b32 v76, v26 offset:64
	ds_read_b32 v77, v26 offset:196
	ds_read_b32 v78, v26 offset:328
	ds_read_b32 v79, v26 offset:460
	ds_read_b32 v80, v26 offset:592
	ds_read_b32 v81, v26 offset:724
	ds_read_b32 v82, v26 offset:856
	ds_read_b32 v83, v26 offset:988
	s_waitcnt lgkmcnt(0)
	v_cvt_pk_bf16_f32 v68, v76, v77
	v_cvt_pk_bf16_f32 v69, v78, v79
	v_cvt_pk_bf16_f32 v70, v80, v81
	v_cvt_pk_bf16_f32 v71, v82, v83
	global_store_dwordx4 v151, v[68:71], s[14:15]
	ds_read_b32 v76, v26 offset:96
	ds_read_b32 v77, v26 offset:228
	ds_read_b32 v78, v26 offset:360
	ds_read_b32 v79, v26 offset:492
	ds_read_b32 v80, v26 offset:624
	ds_read_b32 v81, v26 offset:756
	ds_read_b32 v82, v26 offset:888
	ds_read_b32 v83, v26 offset:1020
	s_waitcnt lgkmcnt(0)
	v_cvt_pk_bf16_f32 v72, v76, v77
	v_cvt_pk_bf16_f32 v73, v78, v79
	v_cvt_pk_bf16_f32 v74, v80, v81
	v_cvt_pk_bf16_f32 v75, v82, v83
	global_store_dwordx4 v152, v[72:75], s[14:15]
	s_add_i32 s20, s20, 1
	s_add_u32 s14, s14, 0xc00
	s_addc_u32 s15, s15, 0
	s_add_i32 s21, s20, 1
	s_cmp_lt_u32 s21, s22
	s_cbranch_scc0 .Lmy_dfw2_olast
	s_mov_b64 s[18:19], s[12:13]
	global_load_dword v100, v148, s[18:19]
	s_add_u32 s18, s18, 0x4000
	s_addc_u32 s19, s19, 0
	global_load_dword v101, v148, s[18:19]
	s_add_u32 s18, s18, 0x4000
	s_addc_u32 s19, s19, 0
	global_load_dword v102, v148, s[18:19]
	s_add_u32 s18, s18, 0x4000
	s_addc_u32 s19, s19, 0
	global_load_dword v103, v148, s[18:19]
	s_add_u32 s18, s18, 0x4000
	s_addc_u32 s19, s19, 0
	global_load_dword v104, v148, s[18:19]
	s_add_u32 s18, s18, 0x4000
	s_addc_u32 s19, s19, 0
	global_load_dword v105, v148, s[18:19]
	s_add_u32 s18, s18, 0x4000
	s_addc_u32 s19, s19, 0
	global_load_dword v106, v148, s[18:19]
	s_add_u32 s18, s18, 0x4000
	s_addc_u32 s19, s19, 0
	global_load_dword v107, v148, s[18:19]
	s_add_u32 s18, s18, 0x4000
	s_addc_u32 s19, s19, 0
	global_load_dword v108, v148, s[18:19]
	s_add_u32 s18, s18, 0x4000
	s_addc_u32 s19, s19, 0
	global_load_dword v109, v148, s[18:19]
	s_add_u32 s18, s18, 0x4000
	s_addc_u32 s19, s19, 0
	global_load_dword v110, v148, s[18:19]
	s_add_u32 s18, s18, 0x4000
	s_addc_u32 s19, s19, 0
	global_load_dword v111, v148, s[18:19]
	s_add_u32 s18, s18, 0x4000
	s_addc_u32 s19, s19, 0
	global_load_dword v112, v148, s[18:19]
	s_add_u32 s18, s18, 0x4000
	s_addc_u32 s19, s19, 0
	global_load_dword v113, v148, s[18:19]
	s_add_u32 s18, s18, 0x4000
	s_addc_u32 s19, s19, 0
	global_load_dword v114, v148, s[18:19]
	s_add_u32 s18, s18, 0x4000
	s_addc_u32 s19, s19, 0
	global_load_dword v115, v148, s[18:19]
	s_add_u32 s18, s18, 0x4000
	s_addc_u32 s19, s19, 0
	global_load_dword v116, v148, s[18:19]
	s_add_u32 s18, s18, 0x4000
	s_addc_u32 s19, s19, 0
	global_load_dword v117, v148, s[18:19]
	s_add_u32 s18, s18, 0x4000
	s_addc_u32 s19, s19, 0
	global_load_dword v118, v148, s[18:19]
	s_add_u32 s18, s18, 0x4000
	s_addc_u32 s19, s19, 0
	global_load_dword v119, v148, s[18:19]
	s_add_u32 s18, s18, 0x4000
	s_addc_u32 s19, s19, 0
	global_load_dword v120, v148, s[18:19]
	s_add_u32 s18, s18, 0x4000
	s_addc_u32 s19, s19, 0
	global_load_dword v121, v148, s[18:19]
	s_add_u32 s18, s18, 0x4000
	s_addc_u32 s19, s19, 0
	global_load_dword v122, v148, s[18:19]
	s_add_u32 s18, s18, 0x4000
	s_addc_u32 s19, s19, 0
	global_load_dword v123, v148, s[18:19]
	s_add_u32 s18, s18, 0x4000
	s_addc_u32 s19, s19, 0
	global_load_dword v124, v148, s[18:19]
	s_add_u32 s18, s18, 0x4000
	s_addc_u32 s19, s19, 0
	global_load_dword v125, v148, s[18:19]
	s_add_u32 s18, s18, 0x4000
	s_addc_u32 s19, s19, 0
	global_load_dword v126, v148, s[18:19]
	s_add_u32 s18, s18, 0x4000
	s_addc_u32 s19, s19, 0
	global_load_dword v127, v148, s[18:19]
	s_add_u32 s18, s18, 0x4000
	s_addc_u32 s19, s19, 0
	global_load_dword v128, v148, s[18:19]
	s_add_u32 s18, s18, 0x4000
	s_addc_u32 s19, s19, 0
	global_load_dword v129, v148, s[18:19]
	s_add_u32 s18, s18, 0x4000
	s_addc_u32 s19, s19, 0
	global_load_dword v130, v148, s[18:19]
	s_add_u32 s18, s18, 0x4000
	s_addc_u32 s19, s19, 0
	global_load_dword v131, v148, s[18:19]
	s_add_u32 s12, s12, 0xc00000
	s_addc_u32 s13, s13, 0
	s_waitcnt vmcnt(32)
	ds_write2_b32 v24, v200, v201 offset1:66
	ds_write2_b32 v24, v202, v203 offset0:132 offset1:198
	ds_write2_b32 v30, v204, v205 offset0:8 offset1:74
	ds_write2_b32 v30, v206, v207 offset0:140 offset1:206
	ds_write2_b32 v31, v208, v209 offset0:16 offset1:82
	ds_write2_b32 v31, v210, v211 offset0:148 offset1:214
	ds_write2_b32 v32, v212, v213 offset0:24 offset1:90
	ds_write2_b32 v32, v214, v215 offset0:156 offset1:222
	ds_write2_b32 v33, v216, v217 offset0:32 offset1:98
	ds_write2_b32 v33, v218, v219 offset0:164 offset1:230
	ds_write2_b32 v34, v220, v221 offset0:40 offset1:106
	ds_write2_b32 v34, v222, v223 offset0:172 offset1:238
	ds_write2_b32 v35, v224, v225 offset0:48 offset1:114
	ds_write2_b32 v35, v226, v227 offset0:180 offset1:246
	ds_write2_b32 v36, v228, v229 offset0:56 offset1:122
	ds_write2_b32 v36, v230, v231 offset0:188 offset1:254
	s_waitcnt lgkmcnt(0)
	ds_read_b32 v76, v26
	ds_read_b32 v77, v26 offset:132
	ds_read_b32 v78, v26 offset:264
	ds_read_b32 v79, v26 offset:396
	ds_read_b32 v80, v26 offset:528
	ds_read_b32 v81, v26 offset:660
	ds_read_b32 v82, v26 offset:792
	ds_read_b32 v83, v26 offset:924
	s_waitcnt lgkmcnt(0)
	v_cvt_pk_bf16_f32 v60, v76, v77
	v_cvt_pk_bf16_f32 v61, v78, v79
	v_cvt_pk_bf16_f32 v62, v80, v81
	v_cvt_pk_bf16_f32 v63, v82, v83
	global_store_dwordx4 v149, v[60:63], s[14:15]
	ds_read_b32 v76, v26 offset:32
	ds_read_b32 v77, v26 offset:164
	ds_read_b32 v78, v26 offset:296
	ds_read_b32 v79, v26 offset:428
	ds_read_b32 v80, v26 offset:560
	ds_read_b32 v81, v26 offset:692
	ds_read_b32 v82, v26 offset:824
	ds_read_b32 v83, v26 offset:956
	s_waitcnt lgkmcnt(0)
	v_cvt_pk_bf16_f32 v64, v76, v77
	v_cvt_pk_bf16_f32 v65, v78, v79
	v_cvt_pk_bf16_f32 v66, v80, v81
	v_cvt_pk_bf16_f32 v67, v82, v83
	global_store_dwordx4 v150, v[64:67], s[14:15]
	ds_read_b32 v76, v26 offset:64
	ds_read_b32 v77, v26 offset:196
	ds_read_b32 v78, v26 offset:328
	ds_read_b32 v79, v26 offset:460
	ds_read_b32 v80, v26 offset:592
	ds_read_b32 v81, v26 offset:724
	ds_read_b32 v82, v26 offset:856
	ds_read_b32 v83, v26 offset:988
	s_waitcnt lgkmcnt(0)
	v_cvt_pk_bf16_f32 v68, v76, v77
	v_cvt_pk_bf16_f32 v69, v78, v79
	v_cvt_pk_bf16_f32 v70, v80, v81
	v_cvt_pk_bf16_f32 v71, v82, v83
	global_store_dwordx4 v151, v[68:71], s[14:15]
	ds_read_b32 v76, v26 offset:96
	ds_read_b32 v77, v26 offset:228
	ds_read_b32 v78, v26 offset:360
	ds_read_b32 v79, v26 offset:492
	ds_read_b32 v80, v26 offset:624
	ds_read_b32 v81, v26 offset:756
	ds_read_b32 v82, v26 offset:888
	ds_read_b32 v83, v26 offset:1020
	s_waitcnt lgkmcnt(0)
	v_cvt_pk_bf16_f32 v72, v76, v77
	v_cvt_pk_bf16_f32 v73, v78, v79
	v_cvt_pk_bf16_f32 v74, v80, v81
	v_cvt_pk_bf16_f32 v75, v82, v83
	global_store_dwordx4 v152, v[72:75], s[14:15]
	s_add_i32 s20, s20, 1
	s_add_u32 s14, s14, 0xc00
	s_addc_u32 s15, s15, 0
	s_branch .Lmy_dfw2_loop
.Lmy_dfw2_elast:
	s_waitcnt vmcnt(0)
	ds_write2_b32 v24, v100, v101 offset1:66
	ds_write2_b32 v24, v102, v103 offset0:132 offset1:198
	ds_write2_b32 v30, v104, v105 offset0:8 offset1:74
	ds_write2_b32 v30, v106, v107 offset0:140 offset1:206
	ds_write2_b32 v31, v108, v109 offset0:16 offset1:82
	ds_write2_b32 v31, v110, v111 offset0:148 offset1:214
	ds_write2_b32 v32, v112, v113 offset0:24 offset1:90
	ds_write2_b32 v32, v114, v115 offset0:156 offset1:222
	ds_write2_b32 v33, v116, v117 offset0:32 offset1:98
	ds_write2_b32 v33, v118, v119 offset0:164 offset1:230
	ds_write2_b32 v34, v120, v121 offset0:40 offset1:106
	ds_write2_b32 v34, v122, v123 offset0:172 offset1:238
	ds_write2_b32 v35, v124, v125 offset0:48 offset1:114
	ds_write2_b32 v35, v126, v127 offset0:180 offset1:246
	ds_write2_b32 v36, v128, v129 offset0:56 offset1:122
	ds_write2_b32 v36, v130, v131 offset0:188 offset1:254
	s_waitcnt lgkmcnt(0)
	ds_read_b32 v76, v26
	ds_read_b32 v77, v26 offset:132
	ds_read_b32 v78, v26 offset:264
	ds_read_b32 v79, v26 offset:396
	ds_read_b32 v80, v26 offset:528
	ds_read_b32 v81, v26 offset:660
	ds_read_b32 v82, v26 offset:792
	ds_read_b32 v83, v26 offset:924
	s_waitcnt lgkmcnt(0)
	v_cvt_pk_bf16_f32 v60, v76, v77
	v_cvt_pk_bf16_f32 v61, v78, v79
	v_cvt_pk_bf16_f32 v62, v80, v81
	v_cvt_pk_bf16_f32 v63, v82, v83
	global_store_dwordx4 v149, v[60:63], s[14:15]
	ds_read_b32 v76, v26 offset:32
	ds_read_b32 v77, v26 offset:164
	ds_read_b32 v78, v26 offset:296
	ds_read_b32 v79, v26 offset:428
	ds_read_b32 v80, v26 offset:560
	ds_read_b32 v81, v26 offset:692
	ds_read_b32 v82, v26 offset:824
	ds_read_b32 v83, v26 offset:956
	s_waitcnt lgkmcnt(0)
	v_cvt_pk_bf16_f32 v64, v76, v77
	v_cvt_pk_bf16_f32 v65, v78, v79
	v_cvt_pk_bf16_f32 v66, v80, v81
	v_cvt_pk_bf16_f32 v67, v82, v83
	global_store_dwordx4 v150, v[64:67], s[14:15]
	ds_read_b32 v76, v26 offset:64
	ds_read_b32 v77, v26 offset:196
	ds_read_b32 v78, v26 offset:328
	ds_read_b32 v79, v26 offset:460
	ds_read_b32 v80, v26 offset:592
	ds_read_b32 v81, v26 offset:724
	ds_read_b32 v82, v26 offset:856
	ds_read_b32 v83, v26 offset:988
	s_waitcnt lgkmcnt(0)
	v_cvt_pk_bf16_f32 v68, v76, v77
	v_cvt_pk_bf16_f32 v69, v78, v79
	v_cvt_pk_bf16_f32 v70, v80, v81
	v_cvt_pk_bf16_f32 v71, v82, v83
	global_store_dwordx4 v151, v[68:71], s[14:15]
	ds_read_b32 v76, v26 offset:96
	ds_read_b32 v77, v26 offset:228
	ds_read_b32 v78, v26 offset:360
	ds_read_b32 v79, v26 offset:492
	ds_read_b32 v80, v26 offset:624
	ds_read_b32 v81, v26 offset:756
	ds_read_b32 v82, v26 offset:888
	ds_read_b32 v83, v26 offset:1020
	s_waitcnt lgkmcnt(0)
	v_cvt_pk_bf16_f32 v72, v76, v77
	v_cvt_pk_bf16_f32 v73, v78, v79
	v_cvt_pk_bf16_f32 v74, v80, v81
	v_cvt_pk_bf16_f32 v75, v82, v83
	global_store_dwordx4 v152, v[72:75], s[14:15]
	s_add_i32 s20, s20, 1
	s_add_u32 s14, s14, 0xc00
	s_addc_u32 s15, s15, 0
	s_branch .Lmy_dfw2_done
.Lmy_dfw2_olast:
	s_waitcnt vmcnt(0)
	ds_write2_b32 v24, v200, v201 offset1:66
	ds_write2_b32 v24, v202, v203 offset0:132 offset1:198
	ds_write2_b32 v30, v204, v205 offset0:8 offset1:74
	ds_write2_b32 v30, v206, v207 offset0:140 offset1:206
	ds_write2_b32 v31, v208, v209 offset0:16 offset1:82
	ds_write2_b32 v31, v210, v211 offset0:148 offset1:214
	ds_write2_b32 v32, v212, v213 offset0:24 offset1:90
	ds_write2_b32 v32, v214, v215 offset0:156 offset1:222
	ds_write2_b32 v33, v216, v217 offset0:32 offset1:98
	ds_write2_b32 v33, v218, v219 offset0:164 offset1:230
	ds_write2_b32 v34, v220, v221 offset0:40 offset1:106
	ds_write2_b32 v34, v222, v223 offset0:172 offset1:238
	ds_write2_b32 v35, v224, v225 offset0:48 offset1:114
	ds_write2_b32 v35, v226, v227 offset0:180 offset1:246
	ds_write2_b32 v36, v228, v229 offset0:56 offset1:122
	ds_write2_b32 v36, v230, v231 offset0:188 offset1:254
	s_waitcnt lgkmcnt(0)
	ds_read_b32 v76, v26
	ds_read_b32 v77, v26 offset:132
	ds_read_b32 v78, v26 offset:264
	ds_read_b32 v79, v26 offset:396
	ds_read_b32 v80, v26 offset:528
	ds_read_b32 v81, v26 offset:660
	ds_read_b32 v82, v26 offset:792
	ds_read_b32 v83, v26 offset:924
	s_waitcnt lgkmcnt(0)
	v_cvt_pk_bf16_f32 v60, v76, v77
	v_cvt_pk_bf16_f32 v61, v78, v79
	v_cvt_pk_bf16_f32 v62, v80, v81
	v_cvt_pk_bf16_f32 v63, v82, v83
	global_store_dwordx4 v149, v[60:63], s[14:15]
	ds_read_b32 v76, v26 offset:32
	ds_read_b32 v77, v26 offset:164
	ds_read_b32 v78, v26 offset:296
	ds_read_b32 v79, v26 offset:428
	ds_read_b32 v80, v26 offset:560
	ds_read_b32 v81, v26 offset:692
	ds_read_b32 v82, v26 offset:824
	ds_read_b32 v83, v26 offset:956
	s_waitcnt lgkmcnt(0)
	v_cvt_pk_bf16_f32 v64, v76, v77
	v_cvt_pk_bf16_f32 v65, v78, v79
	v_cvt_pk_bf16_f32 v66, v80, v81
	v_cvt_pk_bf16_f32 v67, v82, v83
	global_store_dwordx4 v150, v[64:67], s[14:15]
	ds_read_b32 v76, v26 offset:64
	ds_read_b32 v77, v26 offset:196
	ds_read_b32 v78, v26 offset:328
	ds_read_b32 v79, v26 offset:460
	ds_read_b32 v80, v26 offset:592
	ds_read_b32 v81, v26 offset:724
	ds_read_b32 v82, v26 offset:856
	ds_read_b32 v83, v26 offset:988
	s_waitcnt lgkmcnt(0)
	v_cvt_pk_bf16_f32 v68, v76, v77
	v_cvt_pk_bf16_f32 v69, v78, v79
	v_cvt_pk_bf16_f32 v70, v80, v81
	v_cvt_pk_bf16_f32 v71, v82, v83
	global_store_dwordx4 v151, v[68:71], s[14:15]
	ds_read_b32 v76, v26 offset:96
	ds_read_b32 v77, v26 offset:228
	ds_read_b32 v78, v26 offset:360
	ds_read_b32 v79, v26 offset:492
	ds_read_b32 v80, v26 offset:624
	ds_read_b32 v81, v26 offset:756
	ds_read_b32 v82, v26 offset:888
	ds_read_b32 v83, v26 offset:1020
	s_waitcnt lgkmcnt(0)
	v_cvt_pk_bf16_f32 v72, v76, v77
	v_cvt_pk_bf16_f32 v73, v78, v79
	v_cvt_pk_bf16_f32 v74, v80, v81
	v_cvt_pk_bf16_f32 v75, v82, v83
	global_store_dwordx4 v152, v[72:75], s[14:15]
	s_add_i32 s20, s20, 1
	s_add_u32 s14, s14, 0xc00
	s_addc_u32 s15, s15, 0
.Lmy_dfw2_done:
	s_branch .LBB0_182
.LBB0_128:
	s_or_b64 exec, exec, s[6:7]
	s_waitcnt vmcnt(0)
